# k15b + sample-row 64x64 tiles of P2/P7 (K=2816) staged through LDS with full-line LDS-DMA (source-swizzled), line-aligned split-K
# speedup vs baseline: 1.0233x; 1.0233x over previous
; #define LAS __attribute__((address_space(3)))
; template <class Elem>
; __device__ __forceinline__ void gemm_small64(LAS unsigned char* lds, const bf16* A, const bf16* Bt, int K, int r0, int c0, const Elem& E) {
;     int tid_ = threadIdx.x; asm volatile("" : "+v"(tid_));
;     const int tid = tid_, lane = tid & 63, w = __builtin_amdgcn_readfirstlane(tid >> 6), fr = lane & 15, fq = lane >> 4;
;     const int kw = K >> 3, k0 = w * kw;
;     f32x4 acc[4][4];
; #pragma unroll
;     for (int i = 0; i < 4; ++i)
; #pragma unroll
;         for (int j = 0; j < 4; ++j) acc[i][j] = (f32x4){0.f, 0.f, 0.f, 0.f};
;     const bf16* ap = A + (size_t)(r0 + fr) * K + k0 + 8 * fq;
;     const bf16* bp = Bt + (size_t)(c0 + fr) * K + k0 + 8 * fq;
;     const size_t s16 = (size_t)16 * K;
; #pragma unroll 4
;     for (int ks = 0; ks < kw; ks += 32) {
;         bf16x8 a[4], b[4];
; #pragma unroll
;         for (int i = 0; i < 4; ++i) { a[i] = *(const bf16x8*)(ap + i * s16 + ks); b[i] = *(const bf16x8*)(bp + i * s16 + ks); }
; #pragma unroll
;         for (int rb = 0; rb < 4; ++rb)
; #pragma unroll
;             for (int cb = 0; cb < 4; ++cb) acc[rb][cb] = __builtin_amdgcn_mfma_f32_16x16x32_bf16(b[cb], a[rb], acc[rb][cb], 0, 0, 0);
;     }
.LBB0_393:
	v_mov_b32_e32 v45, v192
	s_and_b32 s6, s3, 0x3c0
	s_and_b32 s8, s5, 0xffffffc0
	v_readfirstlane_b32 s9, v45
	v_and_b32_e32 v46, 15, v45
	s_ashr_i32 s21, s9, 6
	v_or_b32_e32 v0, s6, v46
	s_mov_b32 s101, s21
	s_mul_i32 s22, s21, 0x180
	s_mul_i32 s100, s21, 0x140
	s_addk_i32 s100, 0x100
	s_cmp_lt_u32 s21, 4
	s_cselect_b32 s22, s22, s100
	v_mul_u32_u24_e32 v0, 0xb00, v0
	s_ashr_i32 s23, s22, 31
	v_lshlrev_b32_e32 v0, 1, v0
	s_waitcnt lgkmcnt(0)
	v_mov_b32_e32 v1, v31
	s_addk_i32 s8, 0x4000
	s_lshl_b64 s[22:23], s[22:23], 1
	v_lshl_add_u64 v[0:1], s[14:15], 0, v[0:1]
	v_or_b32_e32 v2, s8, v46
	v_and_b32_e32 v30, 48, v45
	v_lshl_add_u64 v[0:1], v[0:1], 0, s[22:23]
	v_lshl_add_u64 v[32:33], v[0:1], 0, v[30:31]
	v_mad_i64_i32 v[0:1], s[36:37], v2, s11, v[28:29]
	v_lshl_add_u64 v[0:1], v[0:1], 0, s[22:23]
	v_lshl_add_u64 v[36:37], v[0:1], 0, v[30:31]
	s_and_b32 s9, s9, 0xfffffc0
	v_lshrrev_b32_e32 v0, 3, v247
	v_and_b32_e32 v1, 7, v247
	v_lshrrev_b32_e32 v2, 1, v0
	v_xor_b32_e32 v3, v1, v2
	v_xor_b32_e32 v4, 4, v3
	v_mul_u32_u24_e32 v5, 0x1600, v0
	v_lshl_add_u32 v6, v3, 4, v5
	v_lshl_add_u32 v7, v4, 4, v5
	v_mov_b32_e32 v9, 0x1600
	v_mad_u32_u24 v8, v46, v9, v30
	v_sub_co_u32_e32 v10, vcc, v36, v8
	s_nop 1
	v_subbrev_co_u32_e32 v11, vcc, 0, v37, vcc
	v_sub_co_u32_e32 v12, vcc, v32, v8
	s_nop 1
	v_subbrev_co_u32_e32 v13, vcc, 0, v33, vcc
	v_mov_b32_e32 v128, v6
	v_add_u32_e32 v129, 0xb000, v7
	v_add_u32_e32 v130, 0x16000, v6
	v_add_u32_e32 v131, 0x21000, v7
	v_add_u32_e32 v132, 0x2c000, v6
	v_add_u32_e32 v133, 0x37000, v7
	v_add_u32_e32 v134, 0x42000, v6
	v_add_u32_e32 v135, 0x4d000, v7
	v_readfirstlane_b32 s98, v10
	v_readfirstlane_b32 s99, v11
	v_readfirstlane_b32 s22, v12
	v_readfirstlane_b32 s23, v13
	s_nop 4
	s_mul_i32 s100, s101, 0x4400
	v_lshrrev_b32_e32 v15, 1, v46
	v_lshrrev_b32_e32 v16, 4, v30
	v_xor_b32_e32 v16, v16, v15
	v_lshlrev_b32_e32 v17, 7, v46
	v_lshl_add_u32 v17, v16, 4, v17
	v_add_u32_e32 v17, s100, v17
	v_xor_b32_e32 v18, 64, v17
	s_add_i32 m0, s100, 0x0
	s_nop 0
	global_load_lds_dwordx4 v128, s[98:99]
	s_add_i32 m0, s100, 0x400
	s_nop 0
	global_load_lds_dwordx4 v129, s[98:99]
	s_add_i32 m0, s100, 0x800
	s_nop 0
	global_load_lds_dwordx4 v130, s[98:99]
	s_add_i32 m0, s100, 0xc00
	s_nop 0
	global_load_lds_dwordx4 v131, s[98:99]
	s_add_i32 m0, s100, 0x1000
	s_nop 0
	global_load_lds_dwordx4 v132, s[98:99]
	s_add_i32 m0, s100, 0x1400
	s_nop 0
	global_load_lds_dwordx4 v133, s[98:99]
	s_add_i32 m0, s100, 0x1800
	s_nop 0
	global_load_lds_dwordx4 v134, s[98:99]
	s_add_i32 m0, s100, 0x1c00
	s_nop 0
	global_load_lds_dwordx4 v135, s[98:99]
	s_add_i32 m0, s100, 0x2000
	s_nop 0
	global_load_lds_dwordx4 v128, s[22:23]
	s_add_i32 m0, s100, 0x2400
	s_nop 0
	global_load_lds_dwordx4 v129, s[22:23]
	s_add_i32 m0, s100, 0x2800
	s_nop 0
	global_load_lds_dwordx4 v130, s[22:23]
	s_add_i32 m0, s100, 0x2c00
	s_nop 0
	global_load_lds_dwordx4 v131, s[22:23]
	s_add_i32 m0, s100, 0x3000
	s_nop 0
	global_load_lds_dwordx4 v132, s[22:23]
	s_add_i32 m0, s100, 0x3400
	s_nop 0
	global_load_lds_dwordx4 v133, s[22:23]
	s_add_i32 m0, s100, 0x3800
	s_nop 0
	global_load_lds_dwordx4 v134, s[22:23]
	s_add_i32 m0, s100, 0x3c00
	s_nop 0
	global_load_lds_dwordx4 v135, s[22:23]
	s_add_u32 s98, s98, 0x80
	s_addc_u32 s99, s99, 0
	s_add_u32 s22, s22, 0x80
	s_addc_u32 s23, s23, 0
	s_waitcnt vmcnt(0)
	ds_read_b128 v[160:163], v17
	ds_read_b128 v[164:167], v17 offset:2048
	ds_read_b128 v[168:171], v17 offset:4096
	ds_read_b128 v[172:175], v17 offset:6144
	ds_read_b128 v[196:199], v17 offset:8192
	ds_read_b128 v[200:203], v17 offset:10240
	ds_read_b128 v[204:207], v17 offset:12288
	ds_read_b128 v[208:211], v17 offset:14336
	ds_read_b128 v[176:179], v18
	ds_read_b128 v[180:183], v18 offset:2048
	ds_read_b128 v[184:187], v18 offset:4096
	ds_read_b128 v[188:191], v18 offset:6144
	ds_read_b128 v[212:215], v18 offset:8192
	ds_read_b128 v[216:219], v18 offset:10240
	ds_read_b128 v[220:223], v18 offset:12288
	ds_read_b128 v[224:227], v18 offset:14336
	s_waitcnt lgkmcnt(0)
	s_add_i32 m0, s100, 0x0
	s_nop 0
	global_load_lds_dwordx4 v128, s[98:99]
	s_add_i32 m0, s100, 0x400
	s_nop 0
	global_load_lds_dwordx4 v129, s[98:99]
	s_add_i32 m0, s100, 0x800
	s_nop 0
	global_load_lds_dwordx4 v130, s[98:99]
	s_add_i32 m0, s100, 0xc00
	s_nop 0
	global_load_lds_dwordx4 v131, s[98:99]
	s_add_i32 m0, s100, 0x1000
	s_nop 0
	global_load_lds_dwordx4 v132, s[98:99]
	s_add_i32 m0, s100, 0x1400
	s_nop 0
	global_load_lds_dwordx4 v133, s[98:99]
	s_add_i32 m0, s100, 0x1800
	s_nop 0
	global_load_lds_dwordx4 v134, s[98:99]
	s_add_i32 m0, s100, 0x1c00
	s_nop 0
	global_load_lds_dwordx4 v135, s[98:99]
	s_add_i32 m0, s100, 0x2000
	s_nop 0
	global_load_lds_dwordx4 v128, s[22:23]
	s_add_i32 m0, s100, 0x2400
	s_nop 0
	global_load_lds_dwordx4 v129, s[22:23]
	s_add_i32 m0, s100, 0x2800
	s_nop 0
	global_load_lds_dwordx4 v130, s[22:23]
	s_add_i32 m0, s100, 0x2c00
	s_nop 0
	global_load_lds_dwordx4 v131, s[22:23]
	s_add_i32 m0, s100, 0x3000
	s_nop 0
	global_load_lds_dwordx4 v132, s[22:23]
	s_add_i32 m0, s100, 0x3400
	s_nop 0
	global_load_lds_dwordx4 v133, s[22:23]
	s_add_i32 m0, s100, 0x3800
	s_nop 0
	global_load_lds_dwordx4 v134, s[22:23]
	s_add_i32 m0, s100, 0x3c00
	s_nop 0
	global_load_lds_dwordx4 v135, s[22:23]
	s_add_u32 s98, s98, 0x80
	s_addc_u32 s99, s99, 0
	s_add_u32 s22, s22, 0x80
	s_addc_u32 s23, s23, 0
	v_mfma_f32_16x16x32_bf16 v[64:67], v[196:199], v[160:163], 0
	v_mfma_f32_16x16x32_bf16 v[68:71], v[200:203], v[160:163], 0
	v_mfma_f32_16x16x32_bf16 v[72:75], v[204:207], v[160:163], 0
	v_mfma_f32_16x16x32_bf16 v[76:79], v[208:211], v[160:163], 0
	v_mfma_f32_16x16x32_bf16 v[80:83], v[196:199], v[164:167], 0
; template <class Elem>
; __device__ __forceinline__ void gemm_small64(LAS unsigned char* lds, const bf16* A, const bf16* Bt, int K, int r0, int c0, const Elem& E) {
;     ...
;     for (int ks = 0; ks < kw; ks += 32) {
;         bf16x8 a[4], b[4];
; #pragma unroll
;         for (int i = 0; i < 4; ++i) { a[i] = *(const bf16x8*)(ap + i * s16 + ks); b[i] = *(const bf16x8*)(bp + i * s16 + ks); }
; #pragma unroll
;         for (int rb = 0; rb < 4; ++rb)
; #pragma unroll
;             for (int cb = 0; cb < 4; ++cb) acc[rb][cb] = __builtin_amdgcn_mfma_f32_16x16x32_bf16(b[cb], a[rb], acc[rb][cb], 0, 0, 0);
;     }
	v_mfma_f32_16x16x32_bf16 v[84:87], v[200:203], v[164:167], 0
	v_mfma_f32_16x16x32_bf16 v[88:91], v[204:207], v[164:167], 0
	v_mfma_f32_16x16x32_bf16 v[92:95], v[208:211], v[164:167], 0
	v_mfma_f32_16x16x32_bf16 v[96:99], v[196:199], v[168:171], 0
	v_mfma_f32_16x16x32_bf16 v[100:103], v[200:203], v[168:171], 0
	v_mfma_f32_16x16x32_bf16 v[104:107], v[204:207], v[168:171], 0
	v_mfma_f32_16x16x32_bf16 v[108:111], v[208:211], v[168:171], 0
	v_mfma_f32_16x16x32_bf16 v[112:115], v[196:199], v[172:175], 0
	v_mfma_f32_16x16x32_bf16 v[116:119], v[200:203], v[172:175], 0
	v_mfma_f32_16x16x32_bf16 v[120:123], v[204:207], v[172:175], 0
	v_mfma_f32_16x16x32_bf16 v[124:127], v[208:211], v[172:175], 0
	v_mfma_f32_16x16x32_bf16 v[64:67], v[212:215], v[176:179], v[64:67]
	v_mfma_f32_16x16x32_bf16 v[68:71], v[216:219], v[176:179], v[68:71]
	v_mfma_f32_16x16x32_bf16 v[72:75], v[220:223], v[176:179], v[72:75]
	v_mfma_f32_16x16x32_bf16 v[76:79], v[224:227], v[176:179], v[76:79]
	v_mfma_f32_16x16x32_bf16 v[80:83], v[212:215], v[180:183], v[80:83]
	v_mfma_f32_16x16x32_bf16 v[84:87], v[216:219], v[180:183], v[84:87]
	v_mfma_f32_16x16x32_bf16 v[88:91], v[220:223], v[180:183], v[88:91]
	v_mfma_f32_16x16x32_bf16 v[92:95], v[224:227], v[180:183], v[92:95]
	v_mfma_f32_16x16x32_bf16 v[96:99], v[212:215], v[184:187], v[96:99]
	v_mfma_f32_16x16x32_bf16 v[100:103], v[216:219], v[184:187], v[100:103]
	v_mfma_f32_16x16x32_bf16 v[104:107], v[220:223], v[184:187], v[104:107]
	v_mfma_f32_16x16x32_bf16 v[108:111], v[224:227], v[184:187], v[108:111]
	v_mfma_f32_16x16x32_bf16 v[112:115], v[212:215], v[188:191], v[112:115]
	v_mfma_f32_16x16x32_bf16 v[116:119], v[216:219], v[188:191], v[116:119]
	v_mfma_f32_16x16x32_bf16 v[120:123], v[220:223], v[188:191], v[120:123]
	v_mfma_f32_16x16x32_bf16 v[124:127], v[224:227], v[188:191], v[124:127]
	s_waitcnt vmcnt(0)
	ds_read_b128 v[160:163], v17
	ds_read_b128 v[164:167], v17 offset:2048
	ds_read_b128 v[168:171], v17 offset:4096
	ds_read_b128 v[172:175], v17 offset:6144
	ds_read_b128 v[196:199], v17 offset:8192
	ds_read_b128 v[200:203], v17 offset:10240
	ds_read_b128 v[204:207], v17 offset:12288
	ds_read_b128 v[208:211], v17 offset:14336
	ds_read_b128 v[176:179], v18
	ds_read_b128 v[180:183], v18 offset:2048
	ds_read_b128 v[184:187], v18 offset:4096
	ds_read_b128 v[188:191], v18 offset:6144
	ds_read_b128 v[212:215], v18 offset:8192
	ds_read_b128 v[216:219], v18 offset:10240
	ds_read_b128 v[220:223], v18 offset:12288
	ds_read_b128 v[224:227], v18 offset:14336
	s_waitcnt lgkmcnt(0)
	s_add_i32 m0, s100, 0x0
	s_nop 0
	global_load_lds_dwordx4 v128, s[98:99]
	s_add_i32 m0, s100, 0x400
	s_nop 0
	global_load_lds_dwordx4 v129, s[98:99]
	s_add_i32 m0, s100, 0x800
	s_nop 0
	global_load_lds_dwordx4 v130, s[98:99]
	s_add_i32 m0, s100, 0xc00
	s_nop 0
	global_load_lds_dwordx4 v131, s[98:99]
	s_add_i32 m0, s100, 0x1000
	s_nop 0
	global_load_lds_dwordx4 v132, s[98:99]
	s_add_i32 m0, s100, 0x1400
	s_nop 0
	global_load_lds_dwordx4 v133, s[98:99]
	s_add_i32 m0, s100, 0x1800
	s_nop 0
	global_load_lds_dwordx4 v134, s[98:99]
	s_add_i32 m0, s100, 0x1c00
	s_nop 0
	global_load_lds_dwordx4 v135, s[98:99]
	s_add_i32 m0, s100, 0x2000
	s_nop 0
	global_load_lds_dwordx4 v128, s[22:23]
	s_add_i32 m0, s100, 0x2400
	s_nop 0
	global_load_lds_dwordx4 v129, s[22:23]
	s_add_i32 m0, s100, 0x2800
	s_nop 0
	global_load_lds_dwordx4 v130, s[22:23]
	s_add_i32 m0, s100, 0x2c00
	s_nop 0
	global_load_lds_dwordx4 v131, s[22:23]
	s_add_i32 m0, s100, 0x3000
	s_nop 0
	global_load_lds_dwordx4 v132, s[22:23]
	s_add_i32 m0, s100, 0x3400
	s_nop 0
	global_load_lds_dwordx4 v133, s[22:23]
	s_add_i32 m0, s100, 0x3800
	s_nop 0
	global_load_lds_dwordx4 v134, s[22:23]
	s_add_i32 m0, s100, 0x3c00
	s_nop 0
	global_load_lds_dwordx4 v135, s[22:23]
	s_add_u32 s98, s98, 0x80
	s_addc_u32 s99, s99, 0
	s_add_u32 s22, s22, 0x80
	s_addc_u32 s23, s23, 0
	v_mfma_f32_16x16x32_bf16 v[64:67], v[196:199], v[160:163], v[64:67]
	v_mfma_f32_16x16x32_bf16 v[68:71], v[200:203], v[160:163], v[68:71]
	v_mfma_f32_16x16x32_bf16 v[72:75], v[204:207], v[160:163], v[72:75]
	v_mfma_f32_16x16x32_bf16 v[76:79], v[208:211], v[160:163], v[76:79]
	v_mfma_f32_16x16x32_bf16 v[80:83], v[196:199], v[164:167], v[80:83]
	v_mfma_f32_16x16x32_bf16 v[84:87], v[200:203], v[164:167], v[84:87]
	v_mfma_f32_16x16x32_bf16 v[88:91], v[204:207], v[164:167], v[88:91]
	v_mfma_f32_16x16x32_bf16 v[92:95], v[208:211], v[164:167], v[92:95]
	v_mfma_f32_16x16x32_bf16 v[96:99], v[196:199], v[168:171], v[96:99]
	v_mfma_f32_16x16x32_bf16 v[100:103], v[200:203], v[168:171], v[100:103]
	v_mfma_f32_16x16x32_bf16 v[104:107], v[204:207], v[168:171], v[104:107]
	v_mfma_f32_16x16x32_bf16 v[108:111], v[208:211], v[168:171], v[108:111]
	v_mfma_f32_16x16x32_bf16 v[112:115], v[196:199], v[172:175], v[112:115]
	v_mfma_f32_16x16x32_bf16 v[116:119], v[200:203], v[172:175], v[116:119]
	v_mfma_f32_16x16x32_bf16 v[120:123], v[204:207], v[172:175], v[120:123]
	v_mfma_f32_16x16x32_bf16 v[124:127], v[208:211], v[172:175], v[124:127]
	v_mfma_f32_16x16x32_bf16 v[64:67], v[212:215], v[176:179], v[64:67]
	v_mfma_f32_16x16x32_bf16 v[68:71], v[216:219], v[176:179], v[68:71]
	v_mfma_f32_16x16x32_bf16 v[72:75], v[220:223], v[176:179], v[72:75]
	v_mfma_f32_16x16x32_bf16 v[76:79], v[224:227], v[176:179], v[76:79]
	v_mfma_f32_16x16x32_bf16 v[80:83], v[212:215], v[180:183], v[80:83]
	v_mfma_f32_16x16x32_bf16 v[84:87], v[216:219], v[180:183], v[84:87]
	v_mfma_f32_16x16x32_bf16 v[88:91], v[220:223], v[180:183], v[88:91]
	v_mfma_f32_16x16x32_bf16 v[92:95], v[224:227], v[180:183], v[92:95]
	v_mfma_f32_16x16x32_bf16 v[96:99], v[212:215], v[184:187], v[96:99]
	v_mfma_f32_16x16x32_bf16 v[100:103], v[216:219], v[184:187], v[100:103]
	v_mfma_f32_16x16x32_bf16 v[104:107], v[220:223], v[184:187], v[104:107]
	v_mfma_f32_16x16x32_bf16 v[108:111], v[224:227], v[184:187], v[108:111]
	v_mfma_f32_16x16x32_bf16 v[112:115], v[212:215], v[188:191], v[112:115]
	v_mfma_f32_16x16x32_bf16 v[116:119], v[216:219], v[188:191], v[116:119]
	v_mfma_f32_16x16x32_bf16 v[120:123], v[220:223], v[188:191], v[120:123]
	v_mfma_f32_16x16x32_bf16 v[124:127], v[224:227], v[188:191], v[124:127]
	s_waitcnt vmcnt(0)
; template <class Elem>
; __device__ __forceinline__ void gemm_small64(LAS unsigned char* lds, const bf16* A, const bf16* Bt, int K, int r0, int c0, const Elem& E) {
;     ...
;     for (int ks = 0; ks < kw; ks += 32) {
;         bf16x8 a[4], b[4];
; #pragma unroll
;         for (int i = 0; i < 4; ++i) { a[i] = *(const bf16x8*)(ap + i * s16 + ks); b[i] = *(const bf16x8*)(bp + i * s16 + ks); }
; #pragma unroll
;         for (int rb = 0; rb < 4; ++rb)
; #pragma unroll
;             for (int cb = 0; cb < 4; ++cb) acc[rb][cb] = __builtin_amdgcn_mfma_f32_16x16x32_bf16(b[cb], a[rb], acc[rb][cb], 0, 0, 0);
;     }
	ds_read_b128 v[160:163], v17
	ds_read_b128 v[164:167], v17 offset:2048
	ds_read_b128 v[168:171], v17 offset:4096
	ds_read_b128 v[172:175], v17 offset:6144
	ds_read_b128 v[196:199], v17 offset:8192
	ds_read_b128 v[200:203], v17 offset:10240
	ds_read_b128 v[204:207], v17 offset:12288
	ds_read_b128 v[208:211], v17 offset:14336
	ds_read_b128 v[176:179], v18
	ds_read_b128 v[180:183], v18 offset:2048
	ds_read_b128 v[184:187], v18 offset:4096
	ds_read_b128 v[188:191], v18 offset:6144
	ds_read_b128 v[212:215], v18 offset:8192
	ds_read_b128 v[216:219], v18 offset:10240
	ds_read_b128 v[220:223], v18 offset:12288
	ds_read_b128 v[224:227], v18 offset:14336
	s_waitcnt lgkmcnt(0)
	s_add_i32 m0, s100, 0x0
	s_nop 0
	global_load_lds_dwordx4 v128, s[98:99]
	s_add_i32 m0, s100, 0x400
	s_nop 0
	global_load_lds_dwordx4 v129, s[98:99]
	s_add_i32 m0, s100, 0x800
	s_nop 0
	global_load_lds_dwordx4 v130, s[98:99]
	s_add_i32 m0, s100, 0xc00
	s_nop 0
	global_load_lds_dwordx4 v131, s[98:99]
	s_add_i32 m0, s100, 0x1000
	s_nop 0
	global_load_lds_dwordx4 v132, s[98:99]
	s_add_i32 m0, s100, 0x1400
	s_nop 0
	global_load_lds_dwordx4 v133, s[98:99]
	s_add_i32 m0, s100, 0x1800
	s_nop 0
	global_load_lds_dwordx4 v134, s[98:99]
	s_add_i32 m0, s100, 0x1c00
	s_nop 0
	global_load_lds_dwordx4 v135, s[98:99]
	s_add_i32 m0, s100, 0x2000
	s_nop 0
	global_load_lds_dwordx4 v128, s[22:23]
	s_add_i32 m0, s100, 0x2400
	s_nop 0
	global_load_lds_dwordx4 v129, s[22:23]
	s_add_i32 m0, s100, 0x2800
	s_nop 0
	global_load_lds_dwordx4 v130, s[22:23]
	s_add_i32 m0, s100, 0x2c00
	s_nop 0
	global_load_lds_dwordx4 v131, s[22:23]
	s_add_i32 m0, s100, 0x3000
	s_nop 0
	global_load_lds_dwordx4 v132, s[22:23]
	s_add_i32 m0, s100, 0x3400
	s_nop 0
	global_load_lds_dwordx4 v133, s[22:23]
	s_add_i32 m0, s100, 0x3800
	s_nop 0
	global_load_lds_dwordx4 v134, s[22:23]
	s_add_i32 m0, s100, 0x3c00
	s_nop 0
	global_load_lds_dwordx4 v135, s[22:23]
	s_add_u32 s98, s98, 0x80
	s_addc_u32 s99, s99, 0
	s_add_u32 s22, s22, 0x80
	s_addc_u32 s23, s23, 0
	v_mfma_f32_16x16x32_bf16 v[64:67], v[196:199], v[160:163], v[64:67]
	v_mfma_f32_16x16x32_bf16 v[68:71], v[200:203], v[160:163], v[68:71]
	v_mfma_f32_16x16x32_bf16 v[72:75], v[204:207], v[160:163], v[72:75]
	v_mfma_f32_16x16x32_bf16 v[76:79], v[208:211], v[160:163], v[76:79]
	v_mfma_f32_16x16x32_bf16 v[80:83], v[196:199], v[164:167], v[80:83]
	v_mfma_f32_16x16x32_bf16 v[84:87], v[200:203], v[164:167], v[84:87]
	v_mfma_f32_16x16x32_bf16 v[88:91], v[204:207], v[164:167], v[88:91]
	v_mfma_f32_16x16x32_bf16 v[92:95], v[208:211], v[164:167], v[92:95]
	v_mfma_f32_16x16x32_bf16 v[96:99], v[196:199], v[168:171], v[96:99]
	v_mfma_f32_16x16x32_bf16 v[100:103], v[200:203], v[168:171], v[100:103]
	v_mfma_f32_16x16x32_bf16 v[104:107], v[204:207], v[168:171], v[104:107]
	v_mfma_f32_16x16x32_bf16 v[108:111], v[208:211], v[168:171], v[108:111]
	v_mfma_f32_16x16x32_bf16 v[112:115], v[196:199], v[172:175], v[112:115]
	v_mfma_f32_16x16x32_bf16 v[116:119], v[200:203], v[172:175], v[116:119]
	v_mfma_f32_16x16x32_bf16 v[120:123], v[204:207], v[172:175], v[120:123]
	v_mfma_f32_16x16x32_bf16 v[124:127], v[208:211], v[172:175], v[124:127]
	v_mfma_f32_16x16x32_bf16 v[64:67], v[212:215], v[176:179], v[64:67]
	v_mfma_f32_16x16x32_bf16 v[68:71], v[216:219], v[176:179], v[68:71]
	v_mfma_f32_16x16x32_bf16 v[72:75], v[220:223], v[176:179], v[72:75]
	v_mfma_f32_16x16x32_bf16 v[76:79], v[224:227], v[176:179], v[76:79]
	v_mfma_f32_16x16x32_bf16 v[80:83], v[212:215], v[180:183], v[80:83]
	v_mfma_f32_16x16x32_bf16 v[84:87], v[216:219], v[180:183], v[84:87]
	v_mfma_f32_16x16x32_bf16 v[88:91], v[220:223], v[180:183], v[88:91]
	v_mfma_f32_16x16x32_bf16 v[92:95], v[224:227], v[180:183], v[92:95]
	v_mfma_f32_16x16x32_bf16 v[96:99], v[212:215], v[184:187], v[96:99]
	v_mfma_f32_16x16x32_bf16 v[100:103], v[216:219], v[184:187], v[100:103]
	v_mfma_f32_16x16x32_bf16 v[104:107], v[220:223], v[184:187], v[104:107]
	v_mfma_f32_16x16x32_bf16 v[108:111], v[224:227], v[184:187], v[108:111]
	v_mfma_f32_16x16x32_bf16 v[112:115], v[212:215], v[188:191], v[112:115]
	v_mfma_f32_16x16x32_bf16 v[116:119], v[216:219], v[188:191], v[116:119]
	v_mfma_f32_16x16x32_bf16 v[120:123], v[220:223], v[188:191], v[120:123]
	v_mfma_f32_16x16x32_bf16 v[124:127], v[224:227], v[188:191], v[124:127]
	s_waitcnt vmcnt(0)
	ds_read_b128 v[160:163], v17
	ds_read_b128 v[164:167], v17 offset:2048
	ds_read_b128 v[168:171], v17 offset:4096
	ds_read_b128 v[172:175], v17 offset:6144
	ds_read_b128 v[196:199], v17 offset:8192
	ds_read_b128 v[200:203], v17 offset:10240
	ds_read_b128 v[204:207], v17 offset:12288
	ds_read_b128 v[208:211], v17 offset:14336
	ds_read_b128 v[176:179], v18
	ds_read_b128 v[180:183], v18 offset:2048
	ds_read_b128 v[184:187], v18 offset:4096
	ds_read_b128 v[188:191], v18 offset:6144
	ds_read_b128 v[212:215], v18 offset:8192
	ds_read_b128 v[216:219], v18 offset:10240
	ds_read_b128 v[220:223], v18 offset:12288
	ds_read_b128 v[224:227], v18 offset:14336
	s_waitcnt lgkmcnt(0)
; template <class Elem>
; __device__ __forceinline__ void gemm_small64(LAS unsigned char* lds, const bf16* A, const bf16* Bt, int K, int r0, int c0, const Elem& E) {
;     ...
;     for (int ks = 0; ks < kw; ks += 32) {
;         bf16x8 a[4], b[4];
; #pragma unroll
;         for (int i = 0; i < 4; ++i) { a[i] = *(const bf16x8*)(ap + i * s16 + ks); b[i] = *(const bf16x8*)(bp + i * s16 + ks); }
; #pragma unroll
;         for (int rb = 0; rb < 4; ++rb)
; #pragma unroll
;             for (int cb = 0; cb < 4; ++cb) acc[rb][cb] = __builtin_amdgcn_mfma_f32_16x16x32_bf16(b[cb], a[rb], acc[rb][cb], 0, 0, 0);
;     }
	s_add_i32 m0, s100, 0x0
	s_nop 0
	global_load_lds_dwordx4 v128, s[98:99]
	s_add_i32 m0, s100, 0x400
	s_nop 0
	global_load_lds_dwordx4 v129, s[98:99]
	s_add_i32 m0, s100, 0x800
	s_nop 0
	global_load_lds_dwordx4 v130, s[98:99]
	s_add_i32 m0, s100, 0xc00
	s_nop 0
	global_load_lds_dwordx4 v131, s[98:99]
	s_add_i32 m0, s100, 0x1000
	s_nop 0
	global_load_lds_dwordx4 v132, s[98:99]
	s_add_i32 m0, s100, 0x1400
	s_nop 0
	global_load_lds_dwordx4 v133, s[98:99]
	s_add_i32 m0, s100, 0x1800
	s_nop 0
	global_load_lds_dwordx4 v134, s[98:99]
	s_add_i32 m0, s100, 0x1c00
	s_nop 0
	global_load_lds_dwordx4 v135, s[98:99]
	s_add_i32 m0, s100, 0x2000
	s_nop 0
	global_load_lds_dwordx4 v128, s[22:23]
	s_add_i32 m0, s100, 0x2400
	s_nop 0
	global_load_lds_dwordx4 v129, s[22:23]
	s_add_i32 m0, s100, 0x2800
	s_nop 0
	global_load_lds_dwordx4 v130, s[22:23]
	s_add_i32 m0, s100, 0x2c00
	s_nop 0
	global_load_lds_dwordx4 v131, s[22:23]
	s_add_i32 m0, s100, 0x3000
	s_nop 0
	global_load_lds_dwordx4 v132, s[22:23]
	s_add_i32 m0, s100, 0x3400
	s_nop 0
	global_load_lds_dwordx4 v133, s[22:23]
	s_add_i32 m0, s100, 0x3800
	s_nop 0
	global_load_lds_dwordx4 v134, s[22:23]
	s_add_i32 m0, s100, 0x3c00
	s_nop 0
	global_load_lds_dwordx4 v135, s[22:23]
	s_add_u32 s98, s98, 0x80
	s_addc_u32 s99, s99, 0
	s_add_u32 s22, s22, 0x80
	s_addc_u32 s23, s23, 0
	v_mfma_f32_16x16x32_bf16 v[64:67], v[196:199], v[160:163], v[64:67]
	v_mfma_f32_16x16x32_bf16 v[68:71], v[200:203], v[160:163], v[68:71]
	v_mfma_f32_16x16x32_bf16 v[72:75], v[204:207], v[160:163], v[72:75]
	v_mfma_f32_16x16x32_bf16 v[76:79], v[208:211], v[160:163], v[76:79]
	v_mfma_f32_16x16x32_bf16 v[80:83], v[196:199], v[164:167], v[80:83]
	v_mfma_f32_16x16x32_bf16 v[84:87], v[200:203], v[164:167], v[84:87]
	v_mfma_f32_16x16x32_bf16 v[88:91], v[204:207], v[164:167], v[88:91]
	v_mfma_f32_16x16x32_bf16 v[92:95], v[208:211], v[164:167], v[92:95]
	v_mfma_f32_16x16x32_bf16 v[96:99], v[196:199], v[168:171], v[96:99]
	v_mfma_f32_16x16x32_bf16 v[100:103], v[200:203], v[168:171], v[100:103]
	v_mfma_f32_16x16x32_bf16 v[104:107], v[204:207], v[168:171], v[104:107]
	v_mfma_f32_16x16x32_bf16 v[108:111], v[208:211], v[168:171], v[108:111]
	v_mfma_f32_16x16x32_bf16 v[112:115], v[196:199], v[172:175], v[112:115]
	v_mfma_f32_16x16x32_bf16 v[116:119], v[200:203], v[172:175], v[116:119]
	v_mfma_f32_16x16x32_bf16 v[120:123], v[204:207], v[172:175], v[120:123]
	v_mfma_f32_16x16x32_bf16 v[124:127], v[208:211], v[172:175], v[124:127]
	v_mfma_f32_16x16x32_bf16 v[64:67], v[212:215], v[176:179], v[64:67]
	v_mfma_f32_16x16x32_bf16 v[68:71], v[216:219], v[176:179], v[68:71]
	v_mfma_f32_16x16x32_bf16 v[72:75], v[220:223], v[176:179], v[72:75]
	v_mfma_f32_16x16x32_bf16 v[76:79], v[224:227], v[176:179], v[76:79]
	v_mfma_f32_16x16x32_bf16 v[80:83], v[212:215], v[180:183], v[80:83]
	v_mfma_f32_16x16x32_bf16 v[84:87], v[216:219], v[180:183], v[84:87]
	v_mfma_f32_16x16x32_bf16 v[88:91], v[220:223], v[180:183], v[88:91]
	v_mfma_f32_16x16x32_bf16 v[92:95], v[224:227], v[180:183], v[92:95]
	v_mfma_f32_16x16x32_bf16 v[96:99], v[212:215], v[184:187], v[96:99]
	v_mfma_f32_16x16x32_bf16 v[100:103], v[216:219], v[184:187], v[100:103]
	v_mfma_f32_16x16x32_bf16 v[104:107], v[220:223], v[184:187], v[104:107]
	v_mfma_f32_16x16x32_bf16 v[108:111], v[224:227], v[184:187], v[108:111]
	v_mfma_f32_16x16x32_bf16 v[112:115], v[212:215], v[188:191], v[112:115]
	v_mfma_f32_16x16x32_bf16 v[116:119], v[216:219], v[188:191], v[116:119]
	v_mfma_f32_16x16x32_bf16 v[120:123], v[220:223], v[188:191], v[120:123]
	v_mfma_f32_16x16x32_bf16 v[124:127], v[224:227], v[188:191], v[124:127]
	s_waitcnt vmcnt(0)
	ds_read_b128 v[160:163], v17
	ds_read_b128 v[164:167], v17 offset:2048
	ds_read_b128 v[168:171], v17 offset:4096
	ds_read_b128 v[172:175], v17 offset:6144
	ds_read_b128 v[196:199], v17 offset:8192
	ds_read_b128 v[200:203], v17 offset:10240
	ds_read_b128 v[204:207], v17 offset:12288
	ds_read_b128 v[208:211], v17 offset:14336
	ds_read_b128 v[176:179], v18
	ds_read_b128 v[180:183], v18 offset:2048
	ds_read_b128 v[184:187], v18 offset:4096
	ds_read_b128 v[188:191], v18 offset:6144
	ds_read_b128 v[212:215], v18 offset:8192
	ds_read_b128 v[216:219], v18 offset:10240
	ds_read_b128 v[220:223], v18 offset:12288
	ds_read_b128 v[224:227], v18 offset:14336
	s_waitcnt lgkmcnt(0)
	s_cmp_lt_u32 s101, 4
	s_cbranch_scc0 .Lsg_p2_nod
	s_add_i32 m0, s100, 0x0
	s_nop 0
	global_load_lds_dwordx4 v128, s[98:99]
	s_add_i32 m0, s100, 0x400
	s_nop 0
	global_load_lds_dwordx4 v129, s[98:99]
	s_add_i32 m0, s100, 0x800
	s_nop 0
	global_load_lds_dwordx4 v130, s[98:99]
	s_add_i32 m0, s100, 0xc00
	s_nop 0
	global_load_lds_dwordx4 v131, s[98:99]
	s_add_i32 m0, s100, 0x1000
	s_nop 0
	global_load_lds_dwordx4 v132, s[98:99]
	s_add_i32 m0, s100, 0x1400
	s_nop 0
	global_load_lds_dwordx4 v133, s[98:99]
	s_add_i32 m0, s100, 0x1800
	s_nop 0
	global_load_lds_dwordx4 v134, s[98:99]
	s_add_i32 m0, s100, 0x1c00
	s_nop 0
	global_load_lds_dwordx4 v135, s[98:99]
	s_add_i32 m0, s100, 0x2000
	s_nop 0
	global_load_lds_dwordx4 v128, s[22:23]
	s_add_i32 m0, s100, 0x2400
	s_nop 0
	global_load_lds_dwordx4 v129, s[22:23]
	s_add_i32 m0, s100, 0x2800
	s_nop 0
	global_load_lds_dwordx4 v130, s[22:23]
	s_add_i32 m0, s100, 0x2c00
	s_nop 0
	global_load_lds_dwordx4 v131, s[22:23]
	s_add_i32 m0, s100, 0x3000
	s_nop 0
	global_load_lds_dwordx4 v132, s[22:23]
	s_add_i32 m0, s100, 0x3400
	s_nop 0
	global_load_lds_dwordx4 v133, s[22:23]
	s_add_i32 m0, s100, 0x3800
	s_nop 0
	global_load_lds_dwordx4 v134, s[22:23]
	s_add_i32 m0, s100, 0x3c00
	s_nop 0
	global_load_lds_dwordx4 v135, s[22:23]
	s_add_u32 s98, s98, 0x80
	s_addc_u32 s99, s99, 0
	s_add_u32 s22, s22, 0x80
	s_addc_u32 s23, s23, 0
; template <class Elem>
; __device__ __forceinline__ void gemm_small64(LAS unsigned char* lds, const bf16* A, const bf16* Bt, int K, int r0, int c0, const Elem& E) {
;     ...
;     for (int ks = 0; ks < kw; ks += 32) {
;         bf16x8 a[4], b[4];
; #pragma unroll
;         for (int i = 0; i < 4; ++i) { a[i] = *(const bf16x8*)(ap + i * s16 + ks); b[i] = *(const bf16x8*)(bp + i * s16 + ks); }
; #pragma unroll
;         for (int rb = 0; rb < 4; ++rb)
; #pragma unroll
;             for (int cb = 0; cb < 4; ++cb) acc[rb][cb] = __builtin_amdgcn_mfma_f32_16x16x32_bf16(b[cb], a[rb], acc[rb][cb], 0, 0, 0);
;     }
.Lsg_p2_nod:
	v_mfma_f32_16x16x32_bf16 v[64:67], v[196:199], v[160:163], v[64:67]
	v_mfma_f32_16x16x32_bf16 v[68:71], v[200:203], v[160:163], v[68:71]
	v_mfma_f32_16x16x32_bf16 v[72:75], v[204:207], v[160:163], v[72:75]
	v_mfma_f32_16x16x32_bf16 v[76:79], v[208:211], v[160:163], v[76:79]
	v_mfma_f32_16x16x32_bf16 v[80:83], v[196:199], v[164:167], v[80:83]
	v_mfma_f32_16x16x32_bf16 v[84:87], v[200:203], v[164:167], v[84:87]
	v_mfma_f32_16x16x32_bf16 v[88:91], v[204:207], v[164:167], v[88:91]
	v_mfma_f32_16x16x32_bf16 v[92:95], v[208:211], v[164:167], v[92:95]
	v_mfma_f32_16x16x32_bf16 v[96:99], v[196:199], v[168:171], v[96:99]
	v_mfma_f32_16x16x32_bf16 v[100:103], v[200:203], v[168:171], v[100:103]
	v_mfma_f32_16x16x32_bf16 v[104:107], v[204:207], v[168:171], v[104:107]
	v_mfma_f32_16x16x32_bf16 v[108:111], v[208:211], v[168:171], v[108:111]
	v_mfma_f32_16x16x32_bf16 v[112:115], v[196:199], v[172:175], v[112:115]
	v_mfma_f32_16x16x32_bf16 v[116:119], v[200:203], v[172:175], v[116:119]
	v_mfma_f32_16x16x32_bf16 v[120:123], v[204:207], v[172:175], v[120:123]
	v_mfma_f32_16x16x32_bf16 v[124:127], v[208:211], v[172:175], v[124:127]
	v_mfma_f32_16x16x32_bf16 v[64:67], v[212:215], v[176:179], v[64:67]
	v_mfma_f32_16x16x32_bf16 v[68:71], v[216:219], v[176:179], v[68:71]
	v_mfma_f32_16x16x32_bf16 v[72:75], v[220:223], v[176:179], v[72:75]
	v_mfma_f32_16x16x32_bf16 v[76:79], v[224:227], v[176:179], v[76:79]
	v_mfma_f32_16x16x32_bf16 v[80:83], v[212:215], v[180:183], v[80:83]
	v_mfma_f32_16x16x32_bf16 v[84:87], v[216:219], v[180:183], v[84:87]
	v_mfma_f32_16x16x32_bf16 v[88:91], v[220:223], v[180:183], v[88:91]
	v_mfma_f32_16x16x32_bf16 v[92:95], v[224:227], v[180:183], v[92:95]
	v_mfma_f32_16x16x32_bf16 v[96:99], v[212:215], v[184:187], v[96:99]
	v_mfma_f32_16x16x32_bf16 v[100:103], v[216:219], v[184:187], v[100:103]
	v_mfma_f32_16x16x32_bf16 v[104:107], v[220:223], v[184:187], v[104:107]
	v_mfma_f32_16x16x32_bf16 v[108:111], v[224:227], v[184:187], v[108:111]
	v_mfma_f32_16x16x32_bf16 v[112:115], v[212:215], v[188:191], v[112:115]
	v_mfma_f32_16x16x32_bf16 v[116:119], v[216:219], v[188:191], v[116:119]
	v_mfma_f32_16x16x32_bf16 v[120:123], v[220:223], v[188:191], v[120:123]
	v_mfma_f32_16x16x32_bf16 v[124:127], v[224:227], v[188:191], v[124:127]
	s_cmp_lt_u32 s101, 4
	s_cbranch_scc0 .Lsg_p2_done
	s_waitcnt vmcnt(0)
	ds_read_b128 v[160:163], v17
	ds_read_b128 v[164:167], v17 offset:2048
	ds_read_b128 v[168:171], v17 offset:4096
	ds_read_b128 v[172:175], v17 offset:6144
	ds_read_b128 v[196:199], v17 offset:8192
	ds_read_b128 v[200:203], v17 offset:10240
	ds_read_b128 v[204:207], v17 offset:12288
	ds_read_b128 v[208:211], v17 offset:14336
	ds_read_b128 v[176:179], v18
	ds_read_b128 v[180:183], v18 offset:2048
	ds_read_b128 v[184:187], v18 offset:4096
	ds_read_b128 v[188:191], v18 offset:6144
	ds_read_b128 v[212:215], v18 offset:8192
	ds_read_b128 v[216:219], v18 offset:10240
	ds_read_b128 v[220:223], v18 offset:12288
	ds_read_b128 v[224:227], v18 offset:14336
	s_waitcnt lgkmcnt(0)
	v_mfma_f32_16x16x32_bf16 v[64:67], v[196:199], v[160:163], v[64:67]
	v_mfma_f32_16x16x32_bf16 v[68:71], v[200:203], v[160:163], v[68:71]
	v_mfma_f32_16x16x32_bf16 v[72:75], v[204:207], v[160:163], v[72:75]
	v_mfma_f32_16x16x32_bf16 v[76:79], v[208:211], v[160:163], v[76:79]
	v_mfma_f32_16x16x32_bf16 v[80:83], v[196:199], v[164:167], v[80:83]
	v_mfma_f32_16x16x32_bf16 v[84:87], v[200:203], v[164:167], v[84:87]
	v_mfma_f32_16x16x32_bf16 v[88:91], v[204:207], v[164:167], v[88:91]
	v_mfma_f32_16x16x32_bf16 v[92:95], v[208:211], v[164:167], v[92:95]
	v_mfma_f32_16x16x32_bf16 v[96:99], v[196:199], v[168:171], v[96:99]
	v_mfma_f32_16x16x32_bf16 v[100:103], v[200:203], v[168:171], v[100:103]
	v_mfma_f32_16x16x32_bf16 v[104:107], v[204:207], v[168:171], v[104:107]
	v_mfma_f32_16x16x32_bf16 v[108:111], v[208:211], v[168:171], v[108:111]
	v_mfma_f32_16x16x32_bf16 v[112:115], v[196:199], v[172:175], v[112:115]
	v_mfma_f32_16x16x32_bf16 v[116:119], v[200:203], v[172:175], v[116:119]
	v_mfma_f32_16x16x32_bf16 v[120:123], v[204:207], v[172:175], v[120:123]
	v_mfma_f32_16x16x32_bf16 v[124:127], v[208:211], v[172:175], v[124:127]
	v_mfma_f32_16x16x32_bf16 v[64:67], v[212:215], v[176:179], v[64:67]
	v_mfma_f32_16x16x32_bf16 v[68:71], v[216:219], v[176:179], v[68:71]
	v_mfma_f32_16x16x32_bf16 v[72:75], v[220:223], v[176:179], v[72:75]
	v_mfma_f32_16x16x32_bf16 v[76:79], v[224:227], v[176:179], v[76:79]
	v_mfma_f32_16x16x32_bf16 v[80:83], v[212:215], v[180:183], v[80:83]
	v_mfma_f32_16x16x32_bf16 v[84:87], v[216:219], v[180:183], v[84:87]
	v_mfma_f32_16x16x32_bf16 v[88:91], v[220:223], v[180:183], v[88:91]
	v_mfma_f32_16x16x32_bf16 v[92:95], v[224:227], v[180:183], v[92:95]
	v_mfma_f32_16x16x32_bf16 v[96:99], v[212:215], v[184:187], v[96:99]
	v_mfma_f32_16x16x32_bf16 v[100:103], v[216:219], v[184:187], v[100:103]
	v_mfma_f32_16x16x32_bf16 v[104:107], v[220:223], v[184:187], v[104:107]
	v_mfma_f32_16x16x32_bf16 v[108:111], v[224:227], v[184:187], v[108:111]
	v_mfma_f32_16x16x32_bf16 v[112:115], v[212:215], v[188:191], v[112:115]
	v_mfma_f32_16x16x32_bf16 v[116:119], v[216:219], v[188:191], v[116:119]
	v_mfma_f32_16x16x32_bf16 v[120:123], v[220:223], v[188:191], v[120:123]
	v_mfma_f32_16x16x32_bf16 v[124:127], v[224:227], v[188:191], v[124:127]
; #define LAS __attribute__((address_space(3)))
; __device__ __forceinline__ void unpack8(const v4u w, float* f) { unpack2(w.x, f[0], f[1]); unpack2(w.y, f[2], f[3]); unpack2(w.z, f[4], f[5]); unpack2(w.w, f[6], f[7]); }
; __device__ __forceinline__ v4u pack8(const float* f) { v4u w; w.x = cvt_pk_bf16(f[0], f[1]); w.y = cvt_pk_bf16(f[2], f[3]); w.z = cvt_pk_bf16(f[4], f[5]); w.w = cvt_pk_bf16(f[6], f[7]); return w; }
;     __device__ __forceinline__ float elem8(int r, int c, f32x4 a0, f32x4 a1) const { float x[8] = {a0[0], a0[1], a0[2], a0[3], a1[0], a1[1], a1[2], a1[3]}; *(v4u*)(P + (size_t)r * D + c) = pack8(x); return 0.f; }
; template <class Elem>
; __device__ __forceinline__ void gemm_small64(LAS unsigned char* lds, const bf16* A, const bf16* Bt, int K, int r0, int c0, const Elem& E) {
;     ...
;     LAS float* P = (LAS float*)lds;
; #pragma unroll
;     for (int rb = 0; rb < 4; ++rb)
; #pragma unroll
;         for (int cb = 0; cb < 4; ++cb) *(LAS f32x4*)(P + (w * 64 + rb * 16 + fr) * 68 + cb * 16 + 4 * fq) = acc[rb][cb];
;     __syncthreads();
;     const int row = tid >> 3, c8 = (tid & 7) * 8;
;     f32x4 v0 = {0.f, 0.f, 0.f, 0.f}, v1 = {0.f, 0.f, 0.f, 0.f};
; #pragma unroll
;     for (int ww = 0; ww < 8; ++ww) { v0 += *(const LAS f32x4*)(P + (ww * 64 + row) * 68 + c8); v1 += *(const LAS f32x4*)(P + (ww * 64 + row) * 68 + c8 + 4); }
;     float ss = E.elem8(r0 + row, c0 + c8, v0, v1);
;     if (Elem::HAS_SS) { ss += __shfl_xor(ss, 1); ss += __shfl_xor(ss, 2); ss += __shfl_xor(ss, 4); if ((tid & 7) == 0) E.row_ss(r0 + row, c0 >> 6, ss); }
;     __device__ __forceinline__ float elem8(int r, int c, f32x4 a0, f32x4 a1) const {
;         bf16* xp = XB + (size_t)r * D + c; float x[8]; unpack8(*(const v4u*)xp, x);
; #pragma unroll
;         for (int j = 0; j < 4; ++j) { x[j] += a0[j] * alpha; x[4 + j] += a1[j] * alpha; }
;         *(v4u*)xp = pack8(x);
;         float ss = 0.f;
; #pragma unroll
;         for (int j = 0; j < 8; ++j) ss += x[j] * x[j];
;         return ss;
;     }
.Lsg_p2_done:
	v_or_b32_e32 v40, s9, v46
	v_mul_lo_u32 v40, v40, s19
	v_add3_u32 v30, 0, v30, v40
	s_nop 7
	s_nop 7
	ds_write_b128 v30, v[64:67]
	ds_write_b128 v30, v[68:71] offset:64
	ds_write_b128 v30, v[72:75] offset:128
	ds_write_b128 v30, v[76:79] offset:192
	ds_write_b128 v30, v[80:83] offset:4352
	ds_write_b128 v30, v[84:87] offset:4416
	ds_write_b128 v30, v[88:91] offset:4480
	ds_write_b128 v30, v[92:95] offset:4544
	ds_write_b128 v30, v[96:99] offset:8704
	ds_write_b128 v30, v[100:103] offset:8768
	ds_write_b128 v30, v[104:107] offset:8832
	ds_write_b128 v30, v[108:111] offset:8896
	ds_write_b128 v30, v[112:115] offset:13056
	ds_write_b128 v30, v[116:119] offset:13120
	ds_write_b128 v30, v[120:123] offset:13184
	ds_write_b128 v30, v[124:127] offset:13248
	v_and_b32_e32 v32, 7, v45
	v_cmp_eq_u32_e32 vcc, 0, v32
	v_ashrrev_i32_e32 v6, 3, v45
	v_lshlrev_b32_e32 v7, 5, v32
	v_add_u32_e32 v0, s8, v6
	v_ashrrev_i32_e32 v1, 31, v0
	v_lshlrev_b64 v[2:3], 11, v[0:1]
	s_lshl_b32 s8, s6, 1
	v_lshl_add_u64 v[2:3], s[34:35], 0, v[2:3]
	v_lshl_or_b32 v30, v32, 4, s8
	v_lshl_add_u64 v[18:19], v[2:3], 0, v[30:31]
	s_waitcnt lgkmcnt(0)
	s_barrier
	global_load_dwordx4 v[2:5], v[18:19], off
	v_mul_lo_u32 v6, v6, s19
	v_add3_u32 v30, 0, v7, v6
	ds_read_b128 v[6:9], v30
	ds_read_b128 v[10:13], v30 offset:16
	ds_read_b128 v[14:17], v30 offset:17408
	s_waitcnt lgkmcnt(2)
	v_pk_add_f32 v[20:21], v[8:9], 0 op_sel_hi:[1,0]
	v_pk_add_f32 v[22:23], v[6:7], 0 op_sel_hi:[1,0]
	ds_read_b128 v[6:9], v30 offset:17424
	s_waitcnt lgkmcnt(2)
	v_pk_add_f32 v[24:25], v[12:13], 0 op_sel_hi:[1,0]
	v_pk_add_f32 v[26:27], v[10:11], 0 op_sel_hi:[1,0]
	ds_read_b128 v[10:13], v30 offset:34816
	s_waitcnt lgkmcnt(2)
	v_pk_add_f32 v[22:23], v[22:23], v[14:15]
	s_waitcnt lgkmcnt(1)
	v_pk_add_f32 v[24:25], v[24:25], v[8:9]
	v_pk_add_f32 v[26:27], v[26:27], v[6:7]
	ds_read_b128 v[6:9], v30 offset:52224
	v_pk_add_f32 v[20:21], v[20:21], v[16:17]
	ds_read_b128 v[14:17], v30 offset:34832
	s_waitcnt lgkmcnt(2)
	v_pk_add_f32 v[22:23], v[22:23], v[10:11]
	v_pk_add_f32 v[20:21], v[20:21], v[12:13]
	ds_read_b128 v[10:13], v30 offset:52240
	s_waitcnt lgkmcnt(2)
	v_pk_add_f32 v[22:23], v[22:23], v[6:7]
	v_add_u32_e32 v6, 0x11000, v30
	v_pk_add_f32 v[20:21], v[20:21], v[8:9]
	ds_read_b128 v[6:9], v6
	s_waitcnt lgkmcnt(2)
	v_pk_add_f32 v[14:15], v[26:27], v[14:15]
	v_pk_add_f32 v[16:17], v[24:25], v[16:17]
	s_waitcnt lgkmcnt(1)
	v_pk_add_f32 v[14:15], v[14:15], v[10:11]
	v_add_u32_e32 v10, 0x11010, v30
	v_pk_add_f32 v[16:17], v[16:17], v[12:13]
	ds_read_b128 v[10:13], v10
	s_waitcnt lgkmcnt(1)
	v_pk_add_f32 v[22:23], v[22:23], v[6:7]
	v_add_u32_e32 v6, 0x15400, v30
	v_pk_add_f32 v[20:21], v[20:21], v[8:9]
	ds_read_b128 v[6:9], v6
	s_waitcnt lgkmcnt(1)
	v_pk_add_f32 v[14:15], v[14:15], v[10:11]
	v_add_u32_e32 v10, 0x15410, v30
	v_pk_add_f32 v[16:17], v[16:17], v[12:13]
	ds_read_b128 v[10:13], v10
	s_waitcnt lgkmcnt(1)
	v_pk_add_f32 v[22:23], v[22:23], v[6:7]
	v_add_u32_e32 v6, 0x19800, v30
	v_pk_add_f32 v[20:21], v[20:21], v[8:9]
	ds_read_b128 v[6:9], v6
	s_waitcnt lgkmcnt(1)
	v_pk_add_f32 v[26:27], v[14:15], v[10:11]
	v_add_u32_e32 v10, 0x19810, v30
	v_pk_add_f32 v[24:25], v[16:17], v[12:13]
	ds_read_b128 v[10:13], v10
	s_waitcnt lgkmcnt(1)
	v_pk_add_f32 v[22:23], v[22:23], v[6:7]
	v_add_u32_e32 v6, 0x1dc00, v30
	v_add_u32_e32 v14, 0x1dc10, v30
	v_pk_add_f32 v[20:21], v[20:21], v[8:9]
	ds_read_b128 v[6:9], v6
	ds_read_b128 v[14:17], v14
	s_waitcnt lgkmcnt(2)
	v_pk_add_f32 v[10:11], v[26:27], v[10:11]
	v_pk_add_f32 v[12:13], v[24:25], v[12:13]
	s_waitcnt lgkmcnt(1)
	v_pk_add_f32 v[6:7], v[22:23], v[6:7]
	s_waitcnt lgkmcnt(0)
	v_pk_add_f32 v[10:11], v[10:11], v[14:15]
	v_pk_add_f32 v[8:9], v[20:21], v[8:9]
	v_pk_add_f32 v[12:13], v[12:13], v[16:17]
	s_waitcnt vmcnt(0)
	v_lshlrev_b32_e32 v14, 16, v2
	v_and_b32_e32 v15, 0xffff0000, v2
	v_pk_fma_f32 v[6:7], v[6:7], 0.5, v[14:15] op_sel_hi:[1,0,1]
	v_lshlrev_b32_e32 v14, 16, v4
	v_and_b32_e32 v15, 0xffff0000, v4
	v_lshlrev_b32_e32 v2, 16, v3
	v_and_b32_e32 v3, 0xffff0000, v3
	v_lshlrev_b32_e32 v4, 16, v5
	v_and_b32_e32 v5, 0xffff0000, v5
	v_pk_fma_f32 v[2:3], v[8:9], 0.5, v[2:3] op_sel_hi:[1,0,1]
	v_pk_fma_f32 v[8:9], v[12:13], 0.5, v[4:5] op_sel_hi:[1,0,1]
	v_pk_mul_f32 v[4:5], v[6:7], v[6:7]
	v_pk_mul_f32 v[12:13], v[2:3], v[2:3]
	v_add_f32_e32 v4, v4, v5
	v_pk_fma_f32 v[10:11], v[10:11], 0.5, v[14:15] op_sel_hi:[1,0,1]
	v_add_f32_e32 v4, v12, v4
	v_pk_mul_f32 v[14:15], v[10:11], v[10:11]
	v_add_f32_e32 v4, v13, v4
	v_add_f32_e32 v4, v14, v4
	v_pk_mul_f32 v[16:17], v[8:9], v[8:9]
	v_add_f32_e32 v4, v15, v4
	v_add_f32_e32 v4, v16, v4
	v_add_f32_e32 v4, v17, v4
	ds_bpermute_b32 v5, v42, v4
	s_waitcnt lgkmcnt(0)
	v_add_f32_e32 v12, v4, v5
	ds_bpermute_b32 v13, v43, v12
	v_cvt_pk_bf16_f32 v5, v2, v3
	v_cvt_pk_bf16_f32 v4, v6, v7
	v_cvt_pk_bf16_f32 v6, v10, v11
	v_cvt_pk_bf16_f32 v7, v8, v9
	s_waitcnt lgkmcnt(0)
	v_add_f32_e32 v2, v12, v13
	ds_bpermute_b32 v3, v44, v2
	global_store_dwordx4 v[18:19], v[4:7], off
	s_and_saveexec_b64 s[8:9], vcc
	s_cbranch_execz .LBB0_392
	v_lshlrev_b64 v[0:1], 6, v[0:1]
	v_lshl_add_u64 v[0:1], s[44:45], 0, v[0:1]
	s_lshr_b32 s6, s6, 4
	v_lshl_add_u64 v[0:1], v[0:1], 0, s[6:7]
	s_waitcnt lgkmcnt(0)
	v_add_f32_e32 v2, v2, v3
	global_store_dword v[0:1], v2, off
	s_branch .LBB0_392

; #define LAS __attribute__((address_space(3)))
; template <class Elem>
; __device__ __forceinline__ void gemm_small64(LAS unsigned char* lds, const bf16* A, const bf16* Bt, int K, int r0, int c0, const Elem& E) {
;     int tid_ = threadIdx.x; asm volatile("" : "+v"(tid_));
;     const int tid = tid_, lane = tid & 63, w = __builtin_amdgcn_readfirstlane(tid >> 6), fr = lane & 15, fq = lane >> 4;
;     const int kw = K >> 3, k0 = w * kw;
;     f32x4 acc[4][4];
; #pragma unroll
;     for (int i = 0; i < 4; ++i)
; #pragma unroll
;         for (int j = 0; j < 4; ++j) acc[i][j] = (f32x4){0.f, 0.f, 0.f, 0.f};
;     const bf16* ap = A + (size_t)(r0 + fr) * K + k0 + 8 * fq;
;     const bf16* bp = Bt + (size_t)(c0 + fr) * K + k0 + 8 * fq;
;     const size_t s16 = (size_t)16 * K;
; #pragma unroll 4
;     for (int ks = 0; ks < kw; ks += 32) {
;         bf16x8 a[4], b[4];
; #pragma unroll
;         for (int i = 0; i < 4; ++i) { a[i] = *(const bf16x8*)(ap + i * s16 + ks); b[i] = *(const bf16x8*)(bp + i * s16 + ks); }
; #pragma unroll
;         for (int rb = 0; rb < 4; ++rb)
; #pragma unroll
;             for (int cb = 0; cb < 4; ++cb) acc[rb][cb] = __builtin_amdgcn_mfma_f32_16x16x32_bf16(b[cb], a[rb], acc[rb][cb], 0, 0, 0);
;     }
.LBB0_1143:
	v_mov_b32_e32 v45, v192
	s_and_b32 s0, s3, 0x3c0
	s_and_b32 s6, s5, 0xffffffc0
	v_readfirstlane_b32 s7, v45
	v_and_b32_e32 v46, 15, v45
	s_ashr_i32 s19, s7, 6
	v_or_b32_e32 v0, s0, v46
	s_mov_b32 s101, s19
	s_mul_i32 s20, s19, 0x180
	s_mul_i32 s100, s19, 0x140
	s_addk_i32 s100, 0x100
	s_cmp_lt_u32 s19, 4
	s_cselect_b32 s20, s20, s100
	v_mul_u32_u24_e32 v0, 0xb00, v0
	s_ashr_i32 s21, s20, 31
	v_lshlrev_b32_e32 v0, 1, v0
	s_waitcnt lgkmcnt(0)
	v_mov_b32_e32 v1, v31
	s_addk_i32 s6, 0x4000
	s_lshl_b64 s[20:21], s[20:21], 1
	v_lshl_add_u64 v[0:1], s[12:13], 0, v[0:1]
	v_or_b32_e32 v2, s6, v46
	v_and_b32_e32 v30, 48, v45
	v_lshl_add_u64 v[0:1], v[0:1], 0, s[20:21]
	v_lshl_add_u64 v[32:33], v[0:1], 0, v[30:31]
	v_mad_i64_i32 v[0:1], s[22:23], v2, s9, v[28:29]
	v_lshl_add_u64 v[0:1], v[0:1], 0, s[20:21]
	v_lshl_add_u64 v[36:37], v[0:1], 0, v[30:31]
	s_and_b32 s7, s7, 0xfffffc0
	v_lshrrev_b32_e32 v0, 3, v246
	v_and_b32_e32 v1, 7, v246
	v_lshrrev_b32_e32 v2, 1, v0
	v_xor_b32_e32 v3, v1, v2
	v_xor_b32_e32 v4, 4, v3
	v_mul_u32_u24_e32 v5, 0x1600, v0
	v_lshl_add_u32 v6, v3, 4, v5
	v_lshl_add_u32 v7, v4, 4, v5
	v_mov_b32_e32 v9, 0x1600
	v_mad_u32_u24 v8, v46, v9, v30
	v_sub_co_u32_e32 v10, vcc, v36, v8
	s_nop 1
	v_subbrev_co_u32_e32 v11, vcc, 0, v37, vcc
	v_sub_co_u32_e32 v12, vcc, v32, v8
	s_nop 1
	v_subbrev_co_u32_e32 v13, vcc, 0, v33, vcc
	v_mov_b32_e32 v128, v6
	v_add_u32_e32 v129, 0xb000, v7
	v_add_u32_e32 v130, 0x16000, v6
	v_add_u32_e32 v131, 0x21000, v7
	v_add_u32_e32 v132, 0x2c000, v6
	v_add_u32_e32 v133, 0x37000, v7
	v_add_u32_e32 v134, 0x42000, v6
	v_add_u32_e32 v135, 0x4d000, v7
	v_readfirstlane_b32 s98, v10
	v_readfirstlane_b32 s99, v11
	v_readfirstlane_b32 s20, v12
	v_readfirstlane_b32 s21, v13
	s_nop 4
	s_mul_i32 s100, s101, 0x4400
	v_lshrrev_b32_e32 v15, 1, v46
	v_lshrrev_b32_e32 v16, 4, v30
	v_xor_b32_e32 v16, v16, v15
	v_lshlrev_b32_e32 v17, 7, v46
	v_lshl_add_u32 v17, v16, 4, v17
	v_add_u32_e32 v17, s100, v17
	v_xor_b32_e32 v18, 64, v17
	s_add_i32 m0, s100, 0x0
	s_nop 0
	global_load_lds_dwordx4 v128, s[98:99]
	s_add_i32 m0, s100, 0x400
	s_nop 0
	global_load_lds_dwordx4 v129, s[98:99]
	s_add_i32 m0, s100, 0x800
	s_nop 0
	global_load_lds_dwordx4 v130, s[98:99]
	s_add_i32 m0, s100, 0xc00
	s_nop 0
	global_load_lds_dwordx4 v131, s[98:99]
	s_add_i32 m0, s100, 0x1000
	s_nop 0
	global_load_lds_dwordx4 v132, s[98:99]
	s_add_i32 m0, s100, 0x1400
	s_nop 0
	global_load_lds_dwordx4 v133, s[98:99]
	s_add_i32 m0, s100, 0x1800
	s_nop 0
	global_load_lds_dwordx4 v134, s[98:99]
	s_add_i32 m0, s100, 0x1c00
	s_nop 0
	global_load_lds_dwordx4 v135, s[98:99]
	s_add_i32 m0, s100, 0x2000
	s_nop 0
	global_load_lds_dwordx4 v128, s[20:21]
	s_add_i32 m0, s100, 0x2400
	s_nop 0
	global_load_lds_dwordx4 v129, s[20:21]
	s_add_i32 m0, s100, 0x2800
	s_nop 0
	global_load_lds_dwordx4 v130, s[20:21]
	s_add_i32 m0, s100, 0x2c00
	s_nop 0
	global_load_lds_dwordx4 v131, s[20:21]
	s_add_i32 m0, s100, 0x3000
	s_nop 0
	global_load_lds_dwordx4 v132, s[20:21]
	s_add_i32 m0, s100, 0x3400
	s_nop 0
	global_load_lds_dwordx4 v133, s[20:21]
	s_add_i32 m0, s100, 0x3800
	s_nop 0
	global_load_lds_dwordx4 v134, s[20:21]
	s_add_i32 m0, s100, 0x3c00
	s_nop 0
	global_load_lds_dwordx4 v135, s[20:21]
	s_add_u32 s98, s98, 0x80
	s_addc_u32 s99, s99, 0
	s_add_u32 s20, s20, 0x80
	s_addc_u32 s21, s21, 0
	s_waitcnt vmcnt(0)
	ds_read_b128 v[160:163], v17
	ds_read_b128 v[164:167], v17 offset:2048
	ds_read_b128 v[168:171], v17 offset:4096
	ds_read_b128 v[172:175], v17 offset:6144
	ds_read_b128 v[196:199], v17 offset:8192
	ds_read_b128 v[200:203], v17 offset:10240
	ds_read_b128 v[204:207], v17 offset:12288
	ds_read_b128 v[208:211], v17 offset:14336
	ds_read_b128 v[176:179], v18
	ds_read_b128 v[180:183], v18 offset:2048
	ds_read_b128 v[184:187], v18 offset:4096
	ds_read_b128 v[188:191], v18 offset:6144
	ds_read_b128 v[212:215], v18 offset:8192
	ds_read_b128 v[216:219], v18 offset:10240
	ds_read_b128 v[220:223], v18 offset:12288
	ds_read_b128 v[224:227], v18 offset:14336
	s_waitcnt lgkmcnt(0)
	s_add_i32 m0, s100, 0x0
	s_nop 0
	global_load_lds_dwordx4 v128, s[98:99]
	s_add_i32 m0, s100, 0x400
	s_nop 0
	global_load_lds_dwordx4 v129, s[98:99]
	s_add_i32 m0, s100, 0x800
	s_nop 0
	global_load_lds_dwordx4 v130, s[98:99]
	s_add_i32 m0, s100, 0xc00
	s_nop 0
	global_load_lds_dwordx4 v131, s[98:99]
	s_add_i32 m0, s100, 0x1000
	s_nop 0
	global_load_lds_dwordx4 v132, s[98:99]
	s_add_i32 m0, s100, 0x1400
	s_nop 0
	global_load_lds_dwordx4 v133, s[98:99]
	s_add_i32 m0, s100, 0x1800
	s_nop 0
	global_load_lds_dwordx4 v134, s[98:99]
	s_add_i32 m0, s100, 0x1c00
	s_nop 0
	global_load_lds_dwordx4 v135, s[98:99]
	s_add_i32 m0, s100, 0x2000
	s_nop 0
	global_load_lds_dwordx4 v128, s[20:21]
	s_add_i32 m0, s100, 0x2400
	s_nop 0
	global_load_lds_dwordx4 v129, s[20:21]
	s_add_i32 m0, s100, 0x2800
	s_nop 0
	global_load_lds_dwordx4 v130, s[20:21]
	s_add_i32 m0, s100, 0x2c00
	s_nop 0
	global_load_lds_dwordx4 v131, s[20:21]
	s_add_i32 m0, s100, 0x3000
	s_nop 0
	global_load_lds_dwordx4 v132, s[20:21]
	s_add_i32 m0, s100, 0x3400
	s_nop 0
	global_load_lds_dwordx4 v133, s[20:21]
	s_add_i32 m0, s100, 0x3800
	s_nop 0
	global_load_lds_dwordx4 v134, s[20:21]
	s_add_i32 m0, s100, 0x3c00
	s_nop 0
	global_load_lds_dwordx4 v135, s[20:21]
	s_add_u32 s98, s98, 0x80
	s_addc_u32 s99, s99, 0
	s_add_u32 s20, s20, 0x80
	s_addc_u32 s21, s21, 0
	v_mfma_f32_16x16x32_bf16 v[64:67], v[196:199], v[160:163], 0
	v_mfma_f32_16x16x32_bf16 v[68:71], v[200:203], v[160:163], 0
	v_mfma_f32_16x16x32_bf16 v[72:75], v[204:207], v[160:163], 0
	v_mfma_f32_16x16x32_bf16 v[76:79], v[208:211], v[160:163], 0
	v_mfma_f32_16x16x32_bf16 v[80:83], v[196:199], v[164:167], 0
; template <class Elem>
; __device__ __forceinline__ void gemm_small64(LAS unsigned char* lds, const bf16* A, const bf16* Bt, int K, int r0, int c0, const Elem& E) {
;     ...
;     for (int ks = 0; ks < kw; ks += 32) {
;         bf16x8 a[4], b[4];
; #pragma unroll
;         for (int i = 0; i < 4; ++i) { a[i] = *(const bf16x8*)(ap + i * s16 + ks); b[i] = *(const bf16x8*)(bp + i * s16 + ks); }
; #pragma unroll
;         for (int rb = 0; rb < 4; ++rb)
; #pragma unroll
;             for (int cb = 0; cb < 4; ++cb) acc[rb][cb] = __builtin_amdgcn_mfma_f32_16x16x32_bf16(b[cb], a[rb], acc[rb][cb], 0, 0, 0);
;     }
	v_mfma_f32_16x16x32_bf16 v[84:87], v[200:203], v[164:167], 0
	v_mfma_f32_16x16x32_bf16 v[88:91], v[204:207], v[164:167], 0
	v_mfma_f32_16x16x32_bf16 v[92:95], v[208:211], v[164:167], 0
	v_mfma_f32_16x16x32_bf16 v[96:99], v[196:199], v[168:171], 0
	v_mfma_f32_16x16x32_bf16 v[100:103], v[200:203], v[168:171], 0
	v_mfma_f32_16x16x32_bf16 v[104:107], v[204:207], v[168:171], 0
	v_mfma_f32_16x16x32_bf16 v[108:111], v[208:211], v[168:171], 0
	v_mfma_f32_16x16x32_bf16 v[112:115], v[196:199], v[172:175], 0
	v_mfma_f32_16x16x32_bf16 v[116:119], v[200:203], v[172:175], 0
	v_mfma_f32_16x16x32_bf16 v[120:123], v[204:207], v[172:175], 0
	v_mfma_f32_16x16x32_bf16 v[124:127], v[208:211], v[172:175], 0
	v_mfma_f32_16x16x32_bf16 v[64:67], v[212:215], v[176:179], v[64:67]
	v_mfma_f32_16x16x32_bf16 v[68:71], v[216:219], v[176:179], v[68:71]
	v_mfma_f32_16x16x32_bf16 v[72:75], v[220:223], v[176:179], v[72:75]
	v_mfma_f32_16x16x32_bf16 v[76:79], v[224:227], v[176:179], v[76:79]
	v_mfma_f32_16x16x32_bf16 v[80:83], v[212:215], v[180:183], v[80:83]
	v_mfma_f32_16x16x32_bf16 v[84:87], v[216:219], v[180:183], v[84:87]
	v_mfma_f32_16x16x32_bf16 v[88:91], v[220:223], v[180:183], v[88:91]
	v_mfma_f32_16x16x32_bf16 v[92:95], v[224:227], v[180:183], v[92:95]
	v_mfma_f32_16x16x32_bf16 v[96:99], v[212:215], v[184:187], v[96:99]
	v_mfma_f32_16x16x32_bf16 v[100:103], v[216:219], v[184:187], v[100:103]
	v_mfma_f32_16x16x32_bf16 v[104:107], v[220:223], v[184:187], v[104:107]
	v_mfma_f32_16x16x32_bf16 v[108:111], v[224:227], v[184:187], v[108:111]
	v_mfma_f32_16x16x32_bf16 v[112:115], v[212:215], v[188:191], v[112:115]
	v_mfma_f32_16x16x32_bf16 v[116:119], v[216:219], v[188:191], v[116:119]
	v_mfma_f32_16x16x32_bf16 v[120:123], v[220:223], v[188:191], v[120:123]
	v_mfma_f32_16x16x32_bf16 v[124:127], v[224:227], v[188:191], v[124:127]
	s_waitcnt vmcnt(0)
	ds_read_b128 v[160:163], v17
	ds_read_b128 v[164:167], v17 offset:2048
	ds_read_b128 v[168:171], v17 offset:4096
	ds_read_b128 v[172:175], v17 offset:6144
	ds_read_b128 v[196:199], v17 offset:8192
	ds_read_b128 v[200:203], v17 offset:10240
	ds_read_b128 v[204:207], v17 offset:12288
	ds_read_b128 v[208:211], v17 offset:14336
	ds_read_b128 v[176:179], v18
	ds_read_b128 v[180:183], v18 offset:2048
	ds_read_b128 v[184:187], v18 offset:4096
	ds_read_b128 v[188:191], v18 offset:6144
	ds_read_b128 v[212:215], v18 offset:8192
	ds_read_b128 v[216:219], v18 offset:10240
	ds_read_b128 v[220:223], v18 offset:12288
	ds_read_b128 v[224:227], v18 offset:14336
	s_waitcnt lgkmcnt(0)
	s_add_i32 m0, s100, 0x0
	s_nop 0
	global_load_lds_dwordx4 v128, s[98:99]
	s_add_i32 m0, s100, 0x400
	s_nop 0
	global_load_lds_dwordx4 v129, s[98:99]
	s_add_i32 m0, s100, 0x800
	s_nop 0
	global_load_lds_dwordx4 v130, s[98:99]
	s_add_i32 m0, s100, 0xc00
	s_nop 0
	global_load_lds_dwordx4 v131, s[98:99]
	s_add_i32 m0, s100, 0x1000
	s_nop 0
	global_load_lds_dwordx4 v132, s[98:99]
	s_add_i32 m0, s100, 0x1400
	s_nop 0
	global_load_lds_dwordx4 v133, s[98:99]
	s_add_i32 m0, s100, 0x1800
	s_nop 0
	global_load_lds_dwordx4 v134, s[98:99]
	s_add_i32 m0, s100, 0x1c00
	s_nop 0
	global_load_lds_dwordx4 v135, s[98:99]
	s_add_i32 m0, s100, 0x2000
	s_nop 0
	global_load_lds_dwordx4 v128, s[20:21]
	s_add_i32 m0, s100, 0x2400
	s_nop 0
	global_load_lds_dwordx4 v129, s[20:21]
	s_add_i32 m0, s100, 0x2800
	s_nop 0
	global_load_lds_dwordx4 v130, s[20:21]
	s_add_i32 m0, s100, 0x2c00
	s_nop 0
	global_load_lds_dwordx4 v131, s[20:21]
	s_add_i32 m0, s100, 0x3000
	s_nop 0
	global_load_lds_dwordx4 v132, s[20:21]
	s_add_i32 m0, s100, 0x3400
	s_nop 0
	global_load_lds_dwordx4 v133, s[20:21]
	s_add_i32 m0, s100, 0x3800
	s_nop 0
	global_load_lds_dwordx4 v134, s[20:21]
	s_add_i32 m0, s100, 0x3c00
	s_nop 0
	global_load_lds_dwordx4 v135, s[20:21]
	s_add_u32 s98, s98, 0x80
	s_addc_u32 s99, s99, 0
	s_add_u32 s20, s20, 0x80
	s_addc_u32 s21, s21, 0
	v_mfma_f32_16x16x32_bf16 v[64:67], v[196:199], v[160:163], v[64:67]
	v_mfma_f32_16x16x32_bf16 v[68:71], v[200:203], v[160:163], v[68:71]
	v_mfma_f32_16x16x32_bf16 v[72:75], v[204:207], v[160:163], v[72:75]
	v_mfma_f32_16x16x32_bf16 v[76:79], v[208:211], v[160:163], v[76:79]
	v_mfma_f32_16x16x32_bf16 v[80:83], v[196:199], v[164:167], v[80:83]
	v_mfma_f32_16x16x32_bf16 v[84:87], v[200:203], v[164:167], v[84:87]
	v_mfma_f32_16x16x32_bf16 v[88:91], v[204:207], v[164:167], v[88:91]
	v_mfma_f32_16x16x32_bf16 v[92:95], v[208:211], v[164:167], v[92:95]
	v_mfma_f32_16x16x32_bf16 v[96:99], v[196:199], v[168:171], v[96:99]
	v_mfma_f32_16x16x32_bf16 v[100:103], v[200:203], v[168:171], v[100:103]
	v_mfma_f32_16x16x32_bf16 v[104:107], v[204:207], v[168:171], v[104:107]
	v_mfma_f32_16x16x32_bf16 v[108:111], v[208:211], v[168:171], v[108:111]
	v_mfma_f32_16x16x32_bf16 v[112:115], v[196:199], v[172:175], v[112:115]
	v_mfma_f32_16x16x32_bf16 v[116:119], v[200:203], v[172:175], v[116:119]
	v_mfma_f32_16x16x32_bf16 v[120:123], v[204:207], v[172:175], v[120:123]
	v_mfma_f32_16x16x32_bf16 v[124:127], v[208:211], v[172:175], v[124:127]
	v_mfma_f32_16x16x32_bf16 v[64:67], v[212:215], v[176:179], v[64:67]
	v_mfma_f32_16x16x32_bf16 v[68:71], v[216:219], v[176:179], v[68:71]
	v_mfma_f32_16x16x32_bf16 v[72:75], v[220:223], v[176:179], v[72:75]
	v_mfma_f32_16x16x32_bf16 v[76:79], v[224:227], v[176:179], v[76:79]
	v_mfma_f32_16x16x32_bf16 v[80:83], v[212:215], v[180:183], v[80:83]
	v_mfma_f32_16x16x32_bf16 v[84:87], v[216:219], v[180:183], v[84:87]
	v_mfma_f32_16x16x32_bf16 v[88:91], v[220:223], v[180:183], v[88:91]
	v_mfma_f32_16x16x32_bf16 v[92:95], v[224:227], v[180:183], v[92:95]
	v_mfma_f32_16x16x32_bf16 v[96:99], v[212:215], v[184:187], v[96:99]
	v_mfma_f32_16x16x32_bf16 v[100:103], v[216:219], v[184:187], v[100:103]
	v_mfma_f32_16x16x32_bf16 v[104:107], v[220:223], v[184:187], v[104:107]
	v_mfma_f32_16x16x32_bf16 v[108:111], v[224:227], v[184:187], v[108:111]
	v_mfma_f32_16x16x32_bf16 v[112:115], v[212:215], v[188:191], v[112:115]
	v_mfma_f32_16x16x32_bf16 v[116:119], v[216:219], v[188:191], v[116:119]
	v_mfma_f32_16x16x32_bf16 v[120:123], v[220:223], v[188:191], v[120:123]
	v_mfma_f32_16x16x32_bf16 v[124:127], v[224:227], v[188:191], v[124:127]
	s_waitcnt vmcnt(0)
; template <class Elem>
; __device__ __forceinline__ void gemm_small64(LAS unsigned char* lds, const bf16* A, const bf16* Bt, int K, int r0, int c0, const Elem& E) {
;     ...
;     for (int ks = 0; ks < kw; ks += 32) {
;         bf16x8 a[4], b[4];
; #pragma unroll
;         for (int i = 0; i < 4; ++i) { a[i] = *(const bf16x8*)(ap + i * s16 + ks); b[i] = *(const bf16x8*)(bp + i * s16 + ks); }
; #pragma unroll
;         for (int rb = 0; rb < 4; ++rb)
; #pragma unroll
;             for (int cb = 0; cb < 4; ++cb) acc[rb][cb] = __builtin_amdgcn_mfma_f32_16x16x32_bf16(b[cb], a[rb], acc[rb][cb], 0, 0, 0);
;     }
	ds_read_b128 v[160:163], v17
	ds_read_b128 v[164:167], v17 offset:2048
	ds_read_b128 v[168:171], v17 offset:4096
	ds_read_b128 v[172:175], v17 offset:6144
	ds_read_b128 v[196:199], v17 offset:8192
	ds_read_b128 v[200:203], v17 offset:10240
	ds_read_b128 v[204:207], v17 offset:12288
	ds_read_b128 v[208:211], v17 offset:14336
	ds_read_b128 v[176:179], v18
	ds_read_b128 v[180:183], v18 offset:2048
	ds_read_b128 v[184:187], v18 offset:4096
	ds_read_b128 v[188:191], v18 offset:6144
	ds_read_b128 v[212:215], v18 offset:8192
	ds_read_b128 v[216:219], v18 offset:10240
	ds_read_b128 v[220:223], v18 offset:12288
	ds_read_b128 v[224:227], v18 offset:14336
	s_waitcnt lgkmcnt(0)
	s_add_i32 m0, s100, 0x0
	s_nop 0
	global_load_lds_dwordx4 v128, s[98:99]
	s_add_i32 m0, s100, 0x400
	s_nop 0
	global_load_lds_dwordx4 v129, s[98:99]
	s_add_i32 m0, s100, 0x800
	s_nop 0
	global_load_lds_dwordx4 v130, s[98:99]
	s_add_i32 m0, s100, 0xc00
	s_nop 0
	global_load_lds_dwordx4 v131, s[98:99]
	s_add_i32 m0, s100, 0x1000
	s_nop 0
	global_load_lds_dwordx4 v132, s[98:99]
	s_add_i32 m0, s100, 0x1400
	s_nop 0
	global_load_lds_dwordx4 v133, s[98:99]
	s_add_i32 m0, s100, 0x1800
	s_nop 0
	global_load_lds_dwordx4 v134, s[98:99]
	s_add_i32 m0, s100, 0x1c00
	s_nop 0
	global_load_lds_dwordx4 v135, s[98:99]
	s_add_i32 m0, s100, 0x2000
	s_nop 0
	global_load_lds_dwordx4 v128, s[20:21]
	s_add_i32 m0, s100, 0x2400
	s_nop 0
	global_load_lds_dwordx4 v129, s[20:21]
	s_add_i32 m0, s100, 0x2800
	s_nop 0
	global_load_lds_dwordx4 v130, s[20:21]
	s_add_i32 m0, s100, 0x2c00
	s_nop 0
	global_load_lds_dwordx4 v131, s[20:21]
	s_add_i32 m0, s100, 0x3000
	s_nop 0
	global_load_lds_dwordx4 v132, s[20:21]
	s_add_i32 m0, s100, 0x3400
	s_nop 0
	global_load_lds_dwordx4 v133, s[20:21]
	s_add_i32 m0, s100, 0x3800
	s_nop 0
	global_load_lds_dwordx4 v134, s[20:21]
	s_add_i32 m0, s100, 0x3c00
	s_nop 0
	global_load_lds_dwordx4 v135, s[20:21]
	s_add_u32 s98, s98, 0x80
	s_addc_u32 s99, s99, 0
	s_add_u32 s20, s20, 0x80
	s_addc_u32 s21, s21, 0
	v_mfma_f32_16x16x32_bf16 v[64:67], v[196:199], v[160:163], v[64:67]
	v_mfma_f32_16x16x32_bf16 v[68:71], v[200:203], v[160:163], v[68:71]
	v_mfma_f32_16x16x32_bf16 v[72:75], v[204:207], v[160:163], v[72:75]
	v_mfma_f32_16x16x32_bf16 v[76:79], v[208:211], v[160:163], v[76:79]
	v_mfma_f32_16x16x32_bf16 v[80:83], v[196:199], v[164:167], v[80:83]
	v_mfma_f32_16x16x32_bf16 v[84:87], v[200:203], v[164:167], v[84:87]
	v_mfma_f32_16x16x32_bf16 v[88:91], v[204:207], v[164:167], v[88:91]
	v_mfma_f32_16x16x32_bf16 v[92:95], v[208:211], v[164:167], v[92:95]
	v_mfma_f32_16x16x32_bf16 v[96:99], v[196:199], v[168:171], v[96:99]
	v_mfma_f32_16x16x32_bf16 v[100:103], v[200:203], v[168:171], v[100:103]
	v_mfma_f32_16x16x32_bf16 v[104:107], v[204:207], v[168:171], v[104:107]
	v_mfma_f32_16x16x32_bf16 v[108:111], v[208:211], v[168:171], v[108:111]
	v_mfma_f32_16x16x32_bf16 v[112:115], v[196:199], v[172:175], v[112:115]
	v_mfma_f32_16x16x32_bf16 v[116:119], v[200:203], v[172:175], v[116:119]
	v_mfma_f32_16x16x32_bf16 v[120:123], v[204:207], v[172:175], v[120:123]
	v_mfma_f32_16x16x32_bf16 v[124:127], v[208:211], v[172:175], v[124:127]
	v_mfma_f32_16x16x32_bf16 v[64:67], v[212:215], v[176:179], v[64:67]
	v_mfma_f32_16x16x32_bf16 v[68:71], v[216:219], v[176:179], v[68:71]
	v_mfma_f32_16x16x32_bf16 v[72:75], v[220:223], v[176:179], v[72:75]
	v_mfma_f32_16x16x32_bf16 v[76:79], v[224:227], v[176:179], v[76:79]
	v_mfma_f32_16x16x32_bf16 v[80:83], v[212:215], v[180:183], v[80:83]
	v_mfma_f32_16x16x32_bf16 v[84:87], v[216:219], v[180:183], v[84:87]
	v_mfma_f32_16x16x32_bf16 v[88:91], v[220:223], v[180:183], v[88:91]
	v_mfma_f32_16x16x32_bf16 v[92:95], v[224:227], v[180:183], v[92:95]
	v_mfma_f32_16x16x32_bf16 v[96:99], v[212:215], v[184:187], v[96:99]
	v_mfma_f32_16x16x32_bf16 v[100:103], v[216:219], v[184:187], v[100:103]
	v_mfma_f32_16x16x32_bf16 v[104:107], v[220:223], v[184:187], v[104:107]
	v_mfma_f32_16x16x32_bf16 v[108:111], v[224:227], v[184:187], v[108:111]
	v_mfma_f32_16x16x32_bf16 v[112:115], v[212:215], v[188:191], v[112:115]
	v_mfma_f32_16x16x32_bf16 v[116:119], v[216:219], v[188:191], v[116:119]
	v_mfma_f32_16x16x32_bf16 v[120:123], v[220:223], v[188:191], v[120:123]
	v_mfma_f32_16x16x32_bf16 v[124:127], v[224:227], v[188:191], v[124:127]
	s_waitcnt vmcnt(0)
	ds_read_b128 v[160:163], v17
	ds_read_b128 v[164:167], v17 offset:2048
	ds_read_b128 v[168:171], v17 offset:4096
	ds_read_b128 v[172:175], v17 offset:6144
	ds_read_b128 v[196:199], v17 offset:8192
	ds_read_b128 v[200:203], v17 offset:10240
	ds_read_b128 v[204:207], v17 offset:12288
	ds_read_b128 v[208:211], v17 offset:14336
	ds_read_b128 v[176:179], v18
	ds_read_b128 v[180:183], v18 offset:2048
	ds_read_b128 v[184:187], v18 offset:4096
	ds_read_b128 v[188:191], v18 offset:6144
	ds_read_b128 v[212:215], v18 offset:8192
	ds_read_b128 v[216:219], v18 offset:10240
	ds_read_b128 v[220:223], v18 offset:12288
	ds_read_b128 v[224:227], v18 offset:14336
	s_waitcnt lgkmcnt(0)
; template <class Elem>
; __device__ __forceinline__ void gemm_small64(LAS unsigned char* lds, const bf16* A, const bf16* Bt, int K, int r0, int c0, const Elem& E) {
;     ...
;     const int kw = K >> 3, k0 = w * kw;
;     f32x4 acc[4][4];
; #pragma unroll
;     for (int i = 0; i < 4; ++i)
; #pragma unroll
;         for (int j = 0; j < 4; ++j) acc[i][j] = (f32x4){0.f, 0.f, 0.f, 0.f};
;     const bf16* ap = A + (size_t)(r0 + fr) * K + k0 + 8 * fq;
;     const bf16* bp = Bt + (size_t)(c0 + fr) * K + k0 + 8 * fq;
;     const size_t s16 = (size_t)16 * K;
; #pragma unroll 4
;     for (int ks = 0; ks < kw; ks += 32) {
;         bf16x8 a[4], b[4];
; #pragma unroll
;         for (int i = 0; i < 4; ++i) { a[i] = *(const bf16x8*)(ap + i * s16 + ks); b[i] = *(const bf16x8*)(bp + i * s16 + ks); }
; #pragma unroll
;         for (int rb = 0; rb < 4; ++rb)
; #pragma unroll
;             for (int cb = 0; cb < 4; ++cb) acc[rb][cb] = __builtin_amdgcn_mfma_f32_16x16x32_bf16(b[cb], a[rb], acc[rb][cb], 0, 0, 0);
;     }
	s_add_i32 m0, s100, 0x0
	s_nop 0
	global_load_lds_dwordx4 v128, s[98:99]
	s_add_i32 m0, s100, 0x400
	s_nop 0
	global_load_lds_dwordx4 v129, s[98:99]
	s_add_i32 m0, s100, 0x800
	s_nop 0
	global_load_lds_dwordx4 v130, s[98:99]
	s_add_i32 m0, s100, 0xc00
	s_nop 0
	global_load_lds_dwordx4 v131, s[98:99]
	s_add_i32 m0, s100, 0x1000
	s_nop 0
	global_load_lds_dwordx4 v132, s[98:99]
	s_add_i32 m0, s100, 0x1400
	s_nop 0
	global_load_lds_dwordx4 v133, s[98:99]
	s_add_i32 m0, s100, 0x1800
	s_nop 0
	global_load_lds_dwordx4 v134, s[98:99]
	s_add_i32 m0, s100, 0x1c00
	s_nop 0
	global_load_lds_dwordx4 v135, s[98:99]
	s_add_i32 m0, s100, 0x2000
	s_nop 0
	global_load_lds_dwordx4 v128, s[20:21]
	s_add_i32 m0, s100, 0x2400
	s_nop 0
	global_load_lds_dwordx4 v129, s[20:21]
	s_add_i32 m0, s100, 0x2800
	s_nop 0
	global_load_lds_dwordx4 v130, s[20:21]
	s_add_i32 m0, s100, 0x2c00
	s_nop 0
	global_load_lds_dwordx4 v131, s[20:21]
	s_add_i32 m0, s100, 0x3000
	s_nop 0
	global_load_lds_dwordx4 v132, s[20:21]
	s_add_i32 m0, s100, 0x3400
	s_nop 0
	global_load_lds_dwordx4 v133, s[20:21]
	s_add_i32 m0, s100, 0x3800
	s_nop 0
	global_load_lds_dwordx4 v134, s[20:21]
	s_add_i32 m0, s100, 0x3c00
	s_nop 0
	global_load_lds_dwordx4 v135, s[20:21]
	s_add_u32 s98, s98, 0x80
	s_addc_u32 s99, s99, 0
	s_add_u32 s20, s20, 0x80
	s_addc_u32 s21, s21, 0
	v_mfma_f32_16x16x32_bf16 v[64:67], v[196:199], v[160:163], v[64:67]
	v_mfma_f32_16x16x32_bf16 v[68:71], v[200:203], v[160:163], v[68:71]
	v_mfma_f32_16x16x32_bf16 v[72:75], v[204:207], v[160:163], v[72:75]
	v_mfma_f32_16x16x32_bf16 v[76:79], v[208:211], v[160:163], v[76:79]
	v_mfma_f32_16x16x32_bf16 v[80:83], v[196:199], v[164:167], v[80:83]
	v_mfma_f32_16x16x32_bf16 v[84:87], v[200:203], v[164:167], v[84:87]
	v_mfma_f32_16x16x32_bf16 v[88:91], v[204:207], v[164:167], v[88:91]
	v_mfma_f32_16x16x32_bf16 v[92:95], v[208:211], v[164:167], v[92:95]
	v_mfma_f32_16x16x32_bf16 v[96:99], v[196:199], v[168:171], v[96:99]
	v_mfma_f32_16x16x32_bf16 v[100:103], v[200:203], v[168:171], v[100:103]
	v_mfma_f32_16x16x32_bf16 v[104:107], v[204:207], v[168:171], v[104:107]
	v_mfma_f32_16x16x32_bf16 v[108:111], v[208:211], v[168:171], v[108:111]
	v_mfma_f32_16x16x32_bf16 v[112:115], v[196:199], v[172:175], v[112:115]
	v_mfma_f32_16x16x32_bf16 v[116:119], v[200:203], v[172:175], v[116:119]
	v_mfma_f32_16x16x32_bf16 v[120:123], v[204:207], v[172:175], v[120:123]
	v_mfma_f32_16x16x32_bf16 v[124:127], v[208:211], v[172:175], v[124:127]
	v_mfma_f32_16x16x32_bf16 v[64:67], v[212:215], v[176:179], v[64:67]
	v_mfma_f32_16x16x32_bf16 v[68:71], v[216:219], v[176:179], v[68:71]
	v_mfma_f32_16x16x32_bf16 v[72:75], v[220:223], v[176:179], v[72:75]
	v_mfma_f32_16x16x32_bf16 v[76:79], v[224:227], v[176:179], v[76:79]
	v_mfma_f32_16x16x32_bf16 v[80:83], v[212:215], v[180:183], v[80:83]
	v_mfma_f32_16x16x32_bf16 v[84:87], v[216:219], v[180:183], v[84:87]
	v_mfma_f32_16x16x32_bf16 v[88:91], v[220:223], v[180:183], v[88:91]
	v_mfma_f32_16x16x32_bf16 v[92:95], v[224:227], v[180:183], v[92:95]
	v_mfma_f32_16x16x32_bf16 v[96:99], v[212:215], v[184:187], v[96:99]
	v_mfma_f32_16x16x32_bf16 v[100:103], v[216:219], v[184:187], v[100:103]
	v_mfma_f32_16x16x32_bf16 v[104:107], v[220:223], v[184:187], v[104:107]
	v_mfma_f32_16x16x32_bf16 v[108:111], v[224:227], v[184:187], v[108:111]
	v_mfma_f32_16x16x32_bf16 v[112:115], v[212:215], v[188:191], v[112:115]
	v_mfma_f32_16x16x32_bf16 v[116:119], v[216:219], v[188:191], v[116:119]
	v_mfma_f32_16x16x32_bf16 v[120:123], v[220:223], v[188:191], v[120:123]
	v_mfma_f32_16x16x32_bf16 v[124:127], v[224:227], v[188:191], v[124:127]
	s_waitcnt vmcnt(0)
	ds_read_b128 v[160:163], v17
	ds_read_b128 v[164:167], v17 offset:2048
	ds_read_b128 v[168:171], v17 offset:4096
	ds_read_b128 v[172:175], v17 offset:6144
	ds_read_b128 v[196:199], v17 offset:8192
	ds_read_b128 v[200:203], v17 offset:10240
	ds_read_b128 v[204:207], v17 offset:12288
	ds_read_b128 v[208:211], v17 offset:14336
	ds_read_b128 v[176:179], v18
	ds_read_b128 v[180:183], v18 offset:2048
	ds_read_b128 v[184:187], v18 offset:4096
	ds_read_b128 v[188:191], v18 offset:6144
	ds_read_b128 v[212:215], v18 offset:8192
	ds_read_b128 v[216:219], v18 offset:10240
	ds_read_b128 v[220:223], v18 offset:12288
	ds_read_b128 v[224:227], v18 offset:14336
	s_waitcnt lgkmcnt(0)
	s_cmp_lt_u32 s101, 4
	s_cbranch_scc0 .Lsg_p7_nod
	s_add_i32 m0, s100, 0x0
	s_nop 0
	global_load_lds_dwordx4 v128, s[98:99]
	s_add_i32 m0, s100, 0x400
	s_nop 0
	global_load_lds_dwordx4 v129, s[98:99]
	s_add_i32 m0, s100, 0x800
	s_nop 0
	global_load_lds_dwordx4 v130, s[98:99]
	s_add_i32 m0, s100, 0xc00
	s_nop 0
	global_load_lds_dwordx4 v131, s[98:99]
	s_add_i32 m0, s100, 0x1000
	s_nop 0
	global_load_lds_dwordx4 v132, s[98:99]
	s_add_i32 m0, s100, 0x1400
	s_nop 0
	global_load_lds_dwordx4 v133, s[98:99]
	s_add_i32 m0, s100, 0x1800
	s_nop 0
	global_load_lds_dwordx4 v134, s[98:99]
	s_add_i32 m0, s100, 0x1c00
	s_nop 0
	global_load_lds_dwordx4 v135, s[98:99]
	s_add_i32 m0, s100, 0x2000
	s_nop 0
	global_load_lds_dwordx4 v128, s[20:21]
	s_add_i32 m0, s100, 0x2400
	s_nop 0
	global_load_lds_dwordx4 v129, s[20:21]
	s_add_i32 m0, s100, 0x2800
	s_nop 0
	global_load_lds_dwordx4 v130, s[20:21]
	s_add_i32 m0, s100, 0x2c00
	s_nop 0
	global_load_lds_dwordx4 v131, s[20:21]
	s_add_i32 m0, s100, 0x3000
	s_nop 0
	global_load_lds_dwordx4 v132, s[20:21]
	s_add_i32 m0, s100, 0x3400
	s_nop 0
	global_load_lds_dwordx4 v133, s[20:21]
	s_add_i32 m0, s100, 0x3800
	s_nop 0
	global_load_lds_dwordx4 v134, s[20:21]
	s_add_i32 m0, s100, 0x3c00
	s_nop 0
	global_load_lds_dwordx4 v135, s[20:21]
	s_add_u32 s98, s98, 0x80
	s_addc_u32 s99, s99, 0
	s_add_u32 s20, s20, 0x80
	s_addc_u32 s21, s21, 0

; #define LAS __attribute__((address_space(3)))
; __device__ __forceinline__ void unpack8(const v4u w, float* f) { unpack2(w.x, f[0], f[1]); unpack2(w.y, f[2], f[3]); unpack2(w.z, f[4], f[5]); unpack2(w.w, f[6], f[7]); }
; __device__ __forceinline__ v4u pack8(const float* f) { v4u w; w.x = cvt_pk_bf16(f[0], f[1]); w.y = cvt_pk_bf16(f[2], f[3]); w.z = cvt_pk_bf16(f[4], f[5]); w.w = cvt_pk_bf16(f[6], f[7]); return w; }
;     __device__ __forceinline__ float elem8(int r, int c, f32x4 a0, f32x4 a1) const { float x[8] = {a0[0], a0[1], a0[2], a0[3], a1[0], a1[1], a1[2], a1[3]}; *(v4u*)(P + (size_t)r * D + c) = pack8(x); return 0.f; }
; template <class Elem>
; __device__ __forceinline__ void gemm_small64(LAS unsigned char* lds, const bf16* A, const bf16* Bt, int K, int r0, int c0, const Elem& E) {
;     ...
;     LAS float* P = (LAS float*)lds;
; #pragma unroll
;     for (int rb = 0; rb < 4; ++rb)
; #pragma unroll
;         for (int cb = 0; cb < 4; ++cb) *(LAS f32x4*)(P + (w * 64 + rb * 16 + fr) * 68 + cb * 16 + 4 * fq) = acc[rb][cb];
;     __syncthreads();
;     const int row = tid >> 3, c8 = (tid & 7) * 8;
;     f32x4 v0 = {0.f, 0.f, 0.f, 0.f}, v1 = {0.f, 0.f, 0.f, 0.f};
; #pragma unroll
;     for (int ww = 0; ww < 8; ++ww) { v0 += *(const LAS f32x4*)(P + (ww * 64 + row) * 68 + c8); v1 += *(const LAS f32x4*)(P + (ww * 64 + row) * 68 + c8 + 4); }
;     float ss = E.elem8(r0 + row, c0 + c8, v0, v1);
;     if (Elem::HAS_SS) { ss += __shfl_xor(ss, 1); ss += __shfl_xor(ss, 2); ss += __shfl_xor(ss, 4); if ((tid & 7) == 0) E.row_ss(r0 + row, c0 >> 6, ss); }
;     __syncthreads();
; }
;     __device__ __forceinline__ float elem8(int r, int c, f32x4 a0, f32x4 a1) const {
;         bf16* xp = XB + (size_t)r * D + c; float x[8]; unpack8(*(const v4u*)xp, x);
; #pragma unroll
;         for (int j = 0; j < 4; ++j) { x[j] += a0[j] * alpha; x[4 + j] += a1[j] * alpha; }
;         *(v4u*)xp = pack8(x);
;         float ss = 0.f;
; #pragma unroll
;         for (int j = 0; j < 8; ++j) ss += x[j] * x[j];
;         return ss;
;     }
.Lsg_p7_done:
	v_or_b32_e32 v40, s7, v46
	v_mul_lo_u32 v40, v40, s17
	v_add3_u32 v30, 0, v30, v40
	s_nop 7
	s_nop 7
	ds_write_b128 v30, v[64:67]
	ds_write_b128 v30, v[68:71] offset:64
	ds_write_b128 v30, v[72:75] offset:128
	ds_write_b128 v30, v[76:79] offset:192
	ds_write_b128 v30, v[80:83] offset:4352
	ds_write_b128 v30, v[84:87] offset:4416
	ds_write_b128 v30, v[88:91] offset:4480
	ds_write_b128 v30, v[92:95] offset:4544
	ds_write_b128 v30, v[96:99] offset:8704
	ds_write_b128 v30, v[100:103] offset:8768
	ds_write_b128 v30, v[104:107] offset:8832
	ds_write_b128 v30, v[108:111] offset:8896
	ds_write_b128 v30, v[112:115] offset:13056
	ds_write_b128 v30, v[116:119] offset:13120
	ds_write_b128 v30, v[120:123] offset:13184
	ds_write_b128 v30, v[124:127] offset:13248
	v_and_b32_e32 v32, 7, v45
	v_cmp_eq_u32_e32 vcc, 0, v32
	v_ashrrev_i32_e32 v6, 3, v45
	v_lshlrev_b32_e32 v7, 5, v32
	v_add_u32_e32 v0, s6, v6
	v_ashrrev_i32_e32 v1, 31, v0
	v_lshlrev_b64 v[2:3], 11, v[0:1]
	s_lshl_b32 s6, s0, 1
	v_lshl_add_u64 v[2:3], s[34:35], 0, v[2:3]
	v_lshl_or_b32 v30, v32, 4, s6
	v_lshl_add_u64 v[18:19], v[2:3], 0, v[30:31]
	s_waitcnt lgkmcnt(0)
	s_barrier
	global_load_dwordx4 v[2:5], v[18:19], off
	v_mul_lo_u32 v6, v6, s17
	v_add3_u32 v30, 0, v7, v6
	ds_read_b128 v[6:9], v30
	ds_read_b128 v[10:13], v30 offset:16
	ds_read_b128 v[14:17], v30 offset:17408
	s_waitcnt lgkmcnt(2)
	v_pk_add_f32 v[20:21], v[8:9], 0 op_sel_hi:[1,0]
	v_pk_add_f32 v[22:23], v[6:7], 0 op_sel_hi:[1,0]
	ds_read_b128 v[6:9], v30 offset:17424
	s_waitcnt lgkmcnt(2)
	v_pk_add_f32 v[24:25], v[12:13], 0 op_sel_hi:[1,0]
	v_pk_add_f32 v[26:27], v[10:11], 0 op_sel_hi:[1,0]
	ds_read_b128 v[10:13], v30 offset:34816
	s_waitcnt lgkmcnt(2)
	v_pk_add_f32 v[22:23], v[22:23], v[14:15]
	s_waitcnt lgkmcnt(1)
	v_pk_add_f32 v[24:25], v[24:25], v[8:9]
	v_pk_add_f32 v[26:27], v[26:27], v[6:7]
	ds_read_b128 v[6:9], v30 offset:52224
	v_pk_add_f32 v[20:21], v[20:21], v[16:17]
	ds_read_b128 v[14:17], v30 offset:34832
	s_waitcnt lgkmcnt(2)
	v_pk_add_f32 v[22:23], v[22:23], v[10:11]
	v_pk_add_f32 v[20:21], v[20:21], v[12:13]
	ds_read_b128 v[10:13], v30 offset:52240
	s_waitcnt lgkmcnt(2)
	v_pk_add_f32 v[22:23], v[22:23], v[6:7]
	v_add_u32_e32 v6, 0x11000, v30
	v_pk_add_f32 v[20:21], v[20:21], v[8:9]
	ds_read_b128 v[6:9], v6
	s_waitcnt lgkmcnt(2)
	v_pk_add_f32 v[14:15], v[26:27], v[14:15]
	v_pk_add_f32 v[16:17], v[24:25], v[16:17]
	s_waitcnt lgkmcnt(1)
	v_pk_add_f32 v[14:15], v[14:15], v[10:11]
	v_add_u32_e32 v10, 0x11010, v30
	v_pk_add_f32 v[16:17], v[16:17], v[12:13]
	ds_read_b128 v[10:13], v10
	s_waitcnt lgkmcnt(1)
	v_pk_add_f32 v[22:23], v[22:23], v[6:7]
	v_add_u32_e32 v6, 0x15400, v30
	v_pk_add_f32 v[20:21], v[20:21], v[8:9]
	ds_read_b128 v[6:9], v6
	s_waitcnt lgkmcnt(1)
	v_pk_add_f32 v[14:15], v[14:15], v[10:11]
	v_add_u32_e32 v10, 0x15410, v30
	v_pk_add_f32 v[16:17], v[16:17], v[12:13]
	ds_read_b128 v[10:13], v10
	s_waitcnt lgkmcnt(1)
	v_pk_add_f32 v[22:23], v[22:23], v[6:7]
	v_add_u32_e32 v6, 0x19800, v30
	v_pk_add_f32 v[20:21], v[20:21], v[8:9]
	ds_read_b128 v[6:9], v6
	s_waitcnt lgkmcnt(1)
	v_pk_add_f32 v[26:27], v[14:15], v[10:11]
	v_add_u32_e32 v10, 0x19810, v30
	v_pk_add_f32 v[24:25], v[16:17], v[12:13]
	ds_read_b128 v[10:13], v10
	s_waitcnt lgkmcnt(1)
	v_pk_add_f32 v[22:23], v[22:23], v[6:7]
	v_add_u32_e32 v6, 0x1dc00, v30
	v_add_u32_e32 v14, 0x1dc10, v30
	v_pk_add_f32 v[20:21], v[20:21], v[8:9]
	ds_read_b128 v[6:9], v6
	ds_read_b128 v[14:17], v14
	s_waitcnt lgkmcnt(2)
	v_pk_add_f32 v[10:11], v[26:27], v[10:11]
	v_pk_add_f32 v[12:13], v[24:25], v[12:13]
	s_waitcnt lgkmcnt(1)
	v_pk_add_f32 v[6:7], v[22:23], v[6:7]
	s_waitcnt lgkmcnt(0)
	v_pk_add_f32 v[10:11], v[10:11], v[14:15]
	v_pk_add_f32 v[8:9], v[20:21], v[8:9]
	v_pk_add_f32 v[12:13], v[12:13], v[16:17]
	s_waitcnt vmcnt(0)
	v_lshlrev_b32_e32 v14, 16, v2
	v_and_b32_e32 v15, 0xffff0000, v2
	v_pk_fma_f32 v[6:7], v[6:7], 0.5, v[14:15] op_sel_hi:[1,0,1]
	v_lshlrev_b32_e32 v14, 16, v4
	v_and_b32_e32 v15, 0xffff0000, v4
	v_lshlrev_b32_e32 v2, 16, v3
	v_and_b32_e32 v3, 0xffff0000, v3
	v_lshlrev_b32_e32 v4, 16, v5
	v_and_b32_e32 v5, 0xffff0000, v5
	v_pk_fma_f32 v[2:3], v[8:9], 0.5, v[2:3] op_sel_hi:[1,0,1]
	v_pk_fma_f32 v[8:9], v[12:13], 0.5, v[4:5] op_sel_hi:[1,0,1]
	v_pk_mul_f32 v[4:5], v[6:7], v[6:7]
	v_pk_mul_f32 v[12:13], v[2:3], v[2:3]
	v_add_f32_e32 v4, v4, v5
	v_pk_fma_f32 v[10:11], v[10:11], 0.5, v[14:15] op_sel_hi:[1,0,1]
	v_add_f32_e32 v4, v12, v4
	v_pk_mul_f32 v[14:15], v[10:11], v[10:11]
	v_add_f32_e32 v4, v13, v4
	v_add_f32_e32 v4, v14, v4
	v_pk_mul_f32 v[16:17], v[8:9], v[8:9]
	v_add_f32_e32 v4, v15, v4
	v_add_f32_e32 v4, v16, v4
	v_add_f32_e32 v4, v17, v4
	ds_bpermute_b32 v5, v42, v4
	s_waitcnt lgkmcnt(0)
	v_add_f32_e32 v12, v4, v5
	ds_bpermute_b32 v13, v43, v12
	v_cvt_pk_bf16_f32 v5, v2, v3
	v_cvt_pk_bf16_f32 v4, v6, v7
	v_cvt_pk_bf16_f32 v6, v10, v11
	v_cvt_pk_bf16_f32 v7, v8, v9
	s_waitcnt lgkmcnt(0)
	v_add_f32_e32 v2, v12, v13
	ds_bpermute_b32 v3, v44, v2
	global_store_dwordx4 v[18:19], v[4:7], off
	s_and_saveexec_b64 s[6:7], vcc
	s_cbranch_execz .LBB0_1142
	v_lshlrev_b64 v[0:1], 6, v[0:1]
	v_lshl_add_u64 v[0:1], s[44:45], 0, v[0:1]
	s_lshr_b32 s0, s0, 4
	v_lshl_add_u64 v[0:1], v[0:1], 0, s[0:1]
	s_waitcnt lgkmcnt(0)
	v_add_f32_e32 v2, v2, v3
	global_store_dword v[0:1], v2, off
	s_branch .LBB0_1142

; __global__ void __launch_bounds__(NWAVES * 64, 2) fwd_megakernel(Args args) {
	.amdhsa_kernel _Z14fwd_megakernel4Args
		.amdhsa_group_segment_fixed_size 0
		.amdhsa_private_segment_fixed_size 0
		.amdhsa_kernarg_size 512
		.amdhsa_user_sgpr_count 2
		.amdhsa_user_sgpr_dispatch_ptr 0
		.amdhsa_user_sgpr_queue_ptr 0
		.amdhsa_user_sgpr_kernarg_segment_ptr 1
		.amdhsa_user_sgpr_dispatch_id 0
		.amdhsa_user_sgpr_kernarg_preload_length 0
		.amdhsa_user_sgpr_kernarg_preload_offset 0
		.amdhsa_user_sgpr_private_segment_size 0
		.amdhsa_uses_dynamic_stack 0
		.amdhsa_enable_private_segment 0
		.amdhsa_system_sgpr_workgroup_id_x 1
		.amdhsa_system_sgpr_workgroup_id_y 0
		.amdhsa_system_sgpr_workgroup_id_z 0
		.amdhsa_system_sgpr_workgroup_info 0
		.amdhsa_system_vgpr_workitem_id 2
		.amdhsa_next_free_vgpr 255
		.amdhsa_next_free_sgpr 102
		.amdhsa_accum_offset 256
		.amdhsa_reserve_vcc 1
		.amdhsa_float_round_mode_32 0
		.amdhsa_float_round_mode_16_64 0
		.amdhsa_float_denorm_mode_32 3
		.amdhsa_float_denorm_mode_16_64 3
		.amdhsa_dx10_clamp 1
		.amdhsa_ieee_mode 1
		.amdhsa_fp16_overflow 0
		.amdhsa_tg_split 0
		.amdhsa_exception_fp_ieee_invalid_op 0
		.amdhsa_exception_fp_denorm_src 0
		.amdhsa_exception_fp_ieee_div_zero 0
		.amdhsa_exception_fp_ieee_overflow 0
		.amdhsa_exception_fp_ieee_underflow 0
		.amdhsa_exception_fp_ieee_inexact 0
		.amdhsa_exception_int_div_zero 0
	.end_amdhsa_kernel

; __global__ void __launch_bounds__(NWAVES * 64, 2) fwd_megakernel(Args args) {
amdhsa.kernels:
  - .agpr_count:     0
    .args:
      - .offset:         0
        .size:           256
        .value_kind:     by_value
      - .offset:         256
        .size:           4
        .value_kind:     hidden_block_count_x
      - .offset:         260
        .size:           4
        .value_kind:     hidden_block_count_y
      - .offset:         264
        .size:           4
        .value_kind:     hidden_block_count_z
      - .offset:         268
        .size:           2
        .value_kind:     hidden_group_size_x
      - .offset:         270
        .size:           2
        .value_kind:     hidden_group_size_y
      - .offset:         272
        .size:           2
        .value_kind:     hidden_group_size_z
      - .offset:         274
        .size:           2
        .value_kind:     hidden_remainder_x
      - .offset:         276
        .size:           2
        .value_kind:     hidden_remainder_y
      - .offset:         278
        .size:           2
        .value_kind:     hidden_remainder_z
      - .offset:         296
        .size:           8
        .value_kind:     hidden_global_offset_x
      - .offset:         304
        .size:           8
        .value_kind:     hidden_global_offset_y
      - .offset:         312
        .size:           8
        .value_kind:     hidden_global_offset_z
      - .offset:         320
        .size:           2
        .value_kind:     hidden_grid_dims
      - .offset:         344
        .size:           8
        .value_kind:     hidden_multigrid_sync_arg
      - .offset:         376
        .size:           4
        .value_kind:     hidden_dynamic_lds_size
    .group_segment_fixed_size: 0
    .kernarg_segment_align: 8
    .kernarg_segment_size: 512
    .language:       OpenCL C
    .language_version:
      - 2
      - 0
    .max_flat_workgroup_size: 512
    .name:           _Z14fwd_megakernel4Args
    .private_segment_fixed_size: 0
    .sgpr_count:     108
    .sgpr_spill_count: 13
    .symbol:         _Z14fwd_megakernel4Args.kd
    .uniform_work_group_size: 1
    .uses_dynamic_stack: false
    .vgpr_count:     255
    .vgpr_spill_count: 0
    .wavefront_size: 64
